# in-projection GEMM main loops re-scheduled: double-buffered LDS fragments, global loads and LDS stores interleaved between MFMAs, epilogue after the last MFMA
# speedup vs baseline: 1.6177x; 1.0213x over previous
.LBB0_130:
	v_readlane_b32 s0, v252, 40
	s_add_i32 s0, s6, s0
	v_mov_b32_e32 v85, v218
	s_lshl_b32 s0, s0, 7
	s_lshl_b32 s1, s37, 7
	v_ashrrev_i32_e32 v32, 3, v85
	v_add_u32_e32 v0, s0, v32
	v_ashrrev_i32_e32 v1, 31, v0
	v_lshlrev_b64 v[0:1], 11, v[0:1]
	s_waitcnt vmcnt(3)
	v_lshlrev_b32_e32 v2, 4, v85
	v_lshl_add_u64 v[0:1], s[56:57], 0, v[0:1]
	v_and_b32_e32 v64, 0x70, v2
	v_lshl_add_u64 v[66:67], v[0:1], 0, v[64:65]
	v_add_co_u32_e32 v70, vcc, s12, v66
	v_add_u32_e32 v0, s1, v32
	s_nop 0
	v_addc_co_u32_e32 v71, vcc, 0, v67, vcc
	v_add_co_u32_e32 v72, vcc, s13, v66
	v_ashrrev_i32_e32 v1, 31, v0
	v_readlane_b32 s6, v252, 0
	v_addc_co_u32_e32 v73, vcc, 0, v67, vcc
	v_lshlrev_b64 v[0:1], 11, v[0:1]
	v_readlane_b32 s7, v252, 1
	v_add_co_u32_e32 v74, vcc, s16, v66
	s_nop 0
	v_lshl_add_u64 v[0:1], s[6:7], 0, v[0:1]
	v_addc_co_u32_e32 v75, vcc, 0, v67, vcc
	v_lshl_add_u64 v[68:69], v[0:1], 0, v[64:65]
	global_load_dwordx4 v[0:3], v[66:67], off
	global_load_dwordx4 v[4:7], v[70:71], off
	global_load_dwordx4 v[8:11], v[72:73], off
	global_load_dwordx4 v[12:15], v[74:75], off
	global_load_dwordx4 v[16:19], v[68:69], off
	v_add_co_u32_e32 v76, vcc, s12, v68
	v_lshrrev_b32_e32 v33, 4, v85
	s_nop 0
	v_addc_co_u32_e32 v77, vcc, 0, v69, vcc
	v_add_co_u32_e32 v78, vcc, s13, v68
	global_load_dwordx4 v[20:23], v[76:77], off
	s_nop 0
	v_addc_co_u32_e32 v79, vcc, 0, v69, vcc
	v_add_co_u32_e32 v82, vcc, s16, v68
	global_load_dwordx4 v[24:27], v[78:79], off
	s_nop 0
	v_addc_co_u32_e32 v83, vcc, 0, v69, vcc
	global_load_dwordx4 v[28:31], v[82:83], off
	v_xor_b32_e32 v33, v33, v85
	v_lshlrev_b32_e32 v33, 4, v33
	v_and_b32_e32 v33, 0x70, v33
	v_lshl_or_b32 v88, v32, 7, v33
	global_load_dwordx4 v[98:101], v[66:67], off offset:128
	global_load_dwordx4 v[102:105], v[68:69], off offset:128
	global_load_dwordx4 v[106:109], v[70:71], off offset:128
	global_load_dwordx4 v[110:113], v[72:73], off offset:128
	global_load_dwordx4 v[114:117], v[74:75], off offset:128
	global_load_dwordx4 v[118:121], v[76:77], off offset:128
	global_load_dwordx4 v[122:125], v[78:79], off offset:128
	global_load_dwordx4 v[126:129], v[82:83], off offset:128
	v_and_b32_e32 v64, 31, v85
	v_bfe_u32 v86, v85, 5, 1
	s_waitcnt vmcnt(15)
	ds_write_b128 v88, v[0:3]
	s_waitcnt vmcnt(11)
	ds_write_b128 v88, v[16:19] offset:32768
	ds_write_b128 v88, v[4:7] offset:4096
	ds_write_b128 v88, v[8:11] offset:8192
	ds_write_b128 v88, v[12:15] offset:12288
	s_waitcnt vmcnt(10)
	ds_write_b128 v88, v[20:23] offset:36864
	s_waitcnt vmcnt(9)
	ds_write_b128 v88, v[24:27] offset:40960
	s_waitcnt vmcnt(8)
	ds_write_b128 v88, v[28:31] offset:45056
	s_waitcnt lgkmcnt(0)
	s_barrier
	global_load_dwordx4 v[130:133], v[70:71], off offset:256
	global_load_dwordx4 v[134:137], v[72:73], off offset:256
	global_load_dwordx4 v[138:141], v[66:67], off offset:256
	global_load_dwordx4 v[142:145], v[68:69], off offset:256
	global_load_dwordx4 v[146:149], v[74:75], off offset:256
	global_load_dwordx4 v[150:153], v[76:77], off offset:256
	global_load_dwordx4 v[154:157], v[78:79], off offset:256
	global_load_dwordx4 v[158:161], v[82:83], off offset:256
	v_ashrrev_i32_e32 v2, 1, v85
	v_lshrrev_b32_e32 v0, 5, v85
	v_bfe_u32 v1, v85, 1, 3
	v_and_b32_e32 v87, 0xffffffc0, v2
	v_or_b32_e32 v2, v87, v64
	v_lshlrev_b32_e32 v3, 7, v85
	v_bitop3_b32 v0, v0, v1, 1 bitop3:0x6c
	v_lshlrev_b32_e32 v2, 7, v2
	v_and_b32_e32 v3, 0x2f80, v3
	v_bitop3_b32 v4, v86, v1, 2 bitop3:0x36
	v_lshlrev_b32_e32 v0, 4, v0
	v_bitop3_b32 v5, v86, v1, 4 bitop3:0x36
	v_or_b32_e32 v95, v2, v0
	v_or_b32_e32 v96, v3, v0
	v_lshlrev_b32_e32 v0, 4, v4
	v_bitop3_b32 v1, v86, v1, 6 bitop3:0x36
	v_or_b32_e32 v94, v2, v0
	v_or_b32_e32 v93, v3, v0
	v_lshlrev_b32_e32 v0, 4, v5
	v_or_b32_e32 v92, v2, v0
	v_or_b32_e32 v91, v3, v0
	v_lshlrev_b32_e32 v0, 4, v1
	v_or_b32_e32 v90, v2, v0
	v_or_b32_e32 v89, v3, v0
	ds_read_b128 v[162:165], v95
	ds_read_b128 v[166:169], v96 offset:32768
	ds_read_b128 v[172:175], v95 offset:4096
	ds_read_b128 v[176:179], v96 offset:36864
	ds_read_b128 v[188:191], v94
	ds_read_b128 v[192:195], v93 offset:32768
	ds_read_b128 v[196:199], v94 offset:4096
	ds_read_b128 v[200:203], v93 offset:36864
	s_waitcnt lgkmcnt(4)
	v_mfma_f32_32x32x16_bf16 v[48:63], v[162:165], v[166:169], 0
	v_mfma_f32_32x32x16_bf16 v[32:47], v[162:165], v[176:179], 0
	v_mfma_f32_32x32x16_bf16 v[16:31], v[172:175], v[166:169], 0
	v_mfma_f32_32x32x16_bf16 v[0:15], v[172:175], v[176:179], 0
	ds_read_b128 v[162:165], v92
	ds_read_b128 v[166:169], v91 offset:32768
	ds_read_b128 v[172:175], v92 offset:4096
	ds_read_b128 v[176:179], v91 offset:36864
	s_waitcnt lgkmcnt(4)
	s_waitcnt vmcnt(8)
	v_mfma_f32_32x32x16_bf16 v[48:63], v[188:191], v[192:195], v[48:63]
	ds_write_b128 v88, v[98:101] offset:16384
	v_mfma_f32_32x32x16_bf16 v[32:47], v[188:191], v[200:203], v[32:47]
	ds_write_b128 v88, v[106:109] offset:20480
	v_mfma_f32_32x32x16_bf16 v[16:31], v[196:199], v[192:195], v[16:31]
	ds_write_b128 v88, v[110:113] offset:24576
	v_mfma_f32_32x32x16_bf16 v[0:15], v[196:199], v[200:203], v[0:15]
	ds_write_b128 v88, v[114:117] offset:28672
	ds_read_b128 v[188:191], v90
	ds_read_b128 v[192:195], v89 offset:32768
	ds_read_b128 v[196:199], v90 offset:4096
	ds_read_b128 v[200:203], v89 offset:36864
	s_waitcnt lgkmcnt(8)
	v_mfma_f32_32x32x16_bf16 v[48:63], v[162:165], v[166:169], v[48:63]
	ds_write_b128 v88, v[102:105] offset:49152
	v_mfma_f32_32x32x16_bf16 v[32:47], v[162:165], v[176:179], v[32:47]
	ds_write_b128 v88, v[118:121] offset:53248
	v_mfma_f32_32x32x16_bf16 v[16:31], v[172:175], v[166:169], v[16:31]
	ds_write_b128 v88, v[122:125] offset:57344
	v_mfma_f32_32x32x16_bf16 v[0:15], v[172:175], v[176:179], v[0:15]
	ds_write_b128 v88, v[126:129] offset:61440
	s_waitcnt lgkmcnt(0)
	s_barrier
	ds_read_b128 v[162:165], v95 offset:16384
	ds_read_b128 v[166:169], v96 offset:49152
	ds_read_b128 v[172:175], v95 offset:20480
	ds_read_b128 v[176:179], v96 offset:53248
	v_mfma_f32_32x32x16_bf16 v[48:63], v[188:191], v[192:195], v[48:63]
	global_load_dwordx4 v[98:101], v[66:67], off offset:384
	v_mfma_f32_32x32x16_bf16 v[32:47], v[188:191], v[200:203], v[32:47]
	global_load_dwordx4 v[106:109], v[70:71], off offset:384
	v_mfma_f32_32x32x16_bf16 v[16:31], v[196:199], v[192:195], v[16:31]
	global_load_dwordx4 v[110:113], v[72:73], off offset:384
	v_mfma_f32_32x32x16_bf16 v[0:15], v[196:199], v[200:203], v[0:15]
	global_load_dwordx4 v[114:117], v[74:75], off offset:384
	ds_read_b128 v[188:191], v94 offset:16384
	ds_read_b128 v[192:195], v93 offset:49152
	ds_read_b128 v[196:199], v94 offset:20480
	ds_read_b128 v[200:203], v93 offset:53248
	s_waitcnt lgkmcnt(4)
	v_mfma_f32_32x32x16_bf16 v[48:63], v[162:165], v[166:169], v[48:63]
	global_load_dwordx4 v[102:105], v[68:69], off offset:384
	v_mfma_f32_32x32x16_bf16 v[32:47], v[162:165], v[176:179], v[32:47]
	global_load_dwordx4 v[118:121], v[76:77], off offset:384
	v_mfma_f32_32x32x16_bf16 v[16:31], v[172:175], v[166:169], v[16:31]
	global_load_dwordx4 v[122:125], v[78:79], off offset:384
	v_mfma_f32_32x32x16_bf16 v[0:15], v[172:175], v[176:179], v[0:15]
	global_load_dwordx4 v[126:129], v[82:83], off offset:384
	ds_read_b128 v[162:165], v92 offset:16384
	ds_read_b128 v[166:169], v91 offset:49152
	ds_read_b128 v[172:175], v92 offset:20480
	ds_read_b128 v[176:179], v91 offset:53248
	s_waitcnt lgkmcnt(4)
	s_waitcnt vmcnt(8)
	v_mfma_f32_32x32x16_bf16 v[48:63], v[188:191], v[192:195], v[48:63]
	ds_write_b128 v88, v[138:141]
	v_mfma_f32_32x32x16_bf16 v[32:47], v[188:191], v[200:203], v[32:47]
	ds_write_b128 v88, v[130:133] offset:4096
	v_mfma_f32_32x32x16_bf16 v[16:31], v[196:199], v[192:195], v[16:31]
	ds_write_b128 v88, v[134:137] offset:8192
	v_mfma_f32_32x32x16_bf16 v[0:15], v[196:199], v[200:203], v[0:15]
	ds_write_b128 v88, v[146:149] offset:12288
	ds_read_b128 v[188:191], v90 offset:16384
	ds_read_b128 v[192:195], v89 offset:49152
	ds_read_b128 v[196:199], v90 offset:20480
	ds_read_b128 v[200:203], v89 offset:53248
	s_waitcnt lgkmcnt(8)
	v_mfma_f32_32x32x16_bf16 v[48:63], v[162:165], v[166:169], v[48:63]
	ds_write_b128 v88, v[142:145] offset:32768
	v_mfma_f32_32x32x16_bf16 v[32:47], v[162:165], v[176:179], v[32:47]
	ds_write_b128 v88, v[150:153] offset:36864
	v_mfma_f32_32x32x16_bf16 v[16:31], v[172:175], v[166:169], v[16:31]
	ds_write_b128 v88, v[154:157] offset:40960
	v_mfma_f32_32x32x16_bf16 v[0:15], v[172:175], v[176:179], v[0:15]
	ds_write_b128 v88, v[158:161] offset:45056
	s_waitcnt lgkmcnt(0)
	s_barrier
	ds_read_b128 v[162:165], v95
	ds_read_b128 v[166:169], v96 offset:32768
	ds_read_b128 v[172:175], v95 offset:4096
	ds_read_b128 v[176:179], v96 offset:36864
	v_mfma_f32_32x32x16_bf16 v[48:63], v[188:191], v[192:195], v[48:63]
	global_load_dwordx4 v[138:141], v[66:67], off offset:512
	v_mfma_f32_32x32x16_bf16 v[32:47], v[188:191], v[200:203], v[32:47]
	global_load_dwordx4 v[130:133], v[70:71], off offset:512
	v_mfma_f32_32x32x16_bf16 v[16:31], v[196:199], v[192:195], v[16:31]
	global_load_dwordx4 v[134:137], v[72:73], off offset:512
	v_mfma_f32_32x32x16_bf16 v[0:15], v[196:199], v[200:203], v[0:15]
	global_load_dwordx4 v[146:149], v[74:75], off offset:512
	ds_read_b128 v[188:191], v94
	ds_read_b128 v[192:195], v93 offset:32768
	ds_read_b128 v[196:199], v94 offset:4096
	ds_read_b128 v[200:203], v93 offset:36864
	s_waitcnt lgkmcnt(4)
	v_mfma_f32_32x32x16_bf16 v[48:63], v[162:165], v[166:169], v[48:63]
	global_load_dwordx4 v[142:145], v[68:69], off offset:512
	v_mfma_f32_32x32x16_bf16 v[32:47], v[162:165], v[176:179], v[32:47]
	global_load_dwordx4 v[150:153], v[76:77], off offset:512
	v_mfma_f32_32x32x16_bf16 v[16:31], v[172:175], v[166:169], v[16:31]
	global_load_dwordx4 v[154:157], v[78:79], off offset:512
	v_mfma_f32_32x32x16_bf16 v[0:15], v[172:175], v[176:179], v[0:15]
	global_load_dwordx4 v[158:161], v[82:83], off offset:512
	ds_read_b128 v[162:165], v92
	ds_read_b128 v[166:169], v91 offset:32768
	ds_read_b128 v[172:175], v92 offset:4096
	ds_read_b128 v[176:179], v91 offset:36864
	s_waitcnt lgkmcnt(4)
	s_waitcnt vmcnt(8)
	v_mfma_f32_32x32x16_bf16 v[48:63], v[188:191], v[192:195], v[48:63]
	ds_write_b128 v88, v[98:101] offset:16384
	v_mfma_f32_32x32x16_bf16 v[32:47], v[188:191], v[200:203], v[32:47]
	ds_write_b128 v88, v[106:109] offset:20480
	v_mfma_f32_32x32x16_bf16 v[16:31], v[196:199], v[192:195], v[16:31]
	ds_write_b128 v88, v[110:113] offset:24576
	v_mfma_f32_32x32x16_bf16 v[0:15], v[196:199], v[200:203], v[0:15]
	ds_write_b128 v88, v[114:117] offset:28672
	ds_read_b128 v[188:191], v90
	ds_read_b128 v[192:195], v89 offset:32768
	ds_read_b128 v[196:199], v90 offset:4096
	ds_read_b128 v[200:203], v89 offset:36864
	s_waitcnt lgkmcnt(8)
	v_mfma_f32_32x32x16_bf16 v[48:63], v[162:165], v[166:169], v[48:63]
	ds_write_b128 v88, v[102:105] offset:49152
	v_mfma_f32_32x32x16_bf16 v[32:47], v[162:165], v[176:179], v[32:47]
	ds_write_b128 v88, v[118:121] offset:53248
	v_mfma_f32_32x32x16_bf16 v[16:31], v[172:175], v[166:169], v[16:31]
	ds_write_b128 v88, v[122:125] offset:57344
	v_mfma_f32_32x32x16_bf16 v[0:15], v[172:175], v[176:179], v[0:15]
	ds_write_b128 v88, v[126:129] offset:61440
	s_waitcnt lgkmcnt(0)
	s_barrier
	ds_read_b128 v[162:165], v95 offset:16384
	ds_read_b128 v[166:169], v96 offset:49152
	ds_read_b128 v[172:175], v95 offset:20480
	ds_read_b128 v[176:179], v96 offset:53248
	v_mfma_f32_32x32x16_bf16 v[48:63], v[188:191], v[192:195], v[48:63]
	global_load_dwordx4 v[98:101], v[66:67], off offset:640
	v_mfma_f32_32x32x16_bf16 v[32:47], v[188:191], v[200:203], v[32:47]
	global_load_dwordx4 v[106:109], v[70:71], off offset:640
	v_mfma_f32_32x32x16_bf16 v[16:31], v[196:199], v[192:195], v[16:31]
	global_load_dwordx4 v[110:113], v[72:73], off offset:640
	v_mfma_f32_32x32x16_bf16 v[0:15], v[196:199], v[200:203], v[0:15]
	global_load_dwordx4 v[114:117], v[74:75], off offset:640
	ds_read_b128 v[188:191], v94 offset:16384
	ds_read_b128 v[192:195], v93 offset:49152
	ds_read_b128 v[196:199], v94 offset:20480
	ds_read_b128 v[200:203], v93 offset:53248
	s_waitcnt lgkmcnt(4)
	v_mfma_f32_32x32x16_bf16 v[48:63], v[162:165], v[166:169], v[48:63]
	global_load_dwordx4 v[102:105], v[68:69], off offset:640
	v_mfma_f32_32x32x16_bf16 v[32:47], v[162:165], v[176:179], v[32:47]
	global_load_dwordx4 v[118:121], v[76:77], off offset:640
	v_mfma_f32_32x32x16_bf16 v[16:31], v[172:175], v[166:169], v[16:31]
	global_load_dwordx4 v[122:125], v[78:79], off offset:640
	v_mfma_f32_32x32x16_bf16 v[0:15], v[172:175], v[176:179], v[0:15]
	global_load_dwordx4 v[126:129], v[82:83], off offset:640
	ds_read_b128 v[162:165], v92 offset:16384
	ds_read_b128 v[166:169], v91 offset:49152
	ds_read_b128 v[172:175], v92 offset:20480
	ds_read_b128 v[176:179], v91 offset:53248
	s_waitcnt lgkmcnt(4)
	s_waitcnt vmcnt(8)
	v_mfma_f32_32x32x16_bf16 v[48:63], v[188:191], v[192:195], v[48:63]
	ds_write_b128 v88, v[138:141]
	v_mfma_f32_32x32x16_bf16 v[32:47], v[188:191], v[200:203], v[32:47]
	ds_write_b128 v88, v[130:133] offset:4096
	v_mfma_f32_32x32x16_bf16 v[16:31], v[196:199], v[192:195], v[16:31]
	ds_write_b128 v88, v[134:137] offset:8192
	v_mfma_f32_32x32x16_bf16 v[0:15], v[196:199], v[200:203], v[0:15]
	ds_write_b128 v88, v[146:149] offset:12288
	ds_read_b128 v[188:191], v90 offset:16384
	ds_read_b128 v[192:195], v89 offset:49152
	ds_read_b128 v[196:199], v90 offset:20480
	ds_read_b128 v[200:203], v89 offset:53248
	s_waitcnt lgkmcnt(8)
	v_mfma_f32_32x32x16_bf16 v[48:63], v[162:165], v[166:169], v[48:63]
	ds_write_b128 v88, v[142:145] offset:32768
	v_mfma_f32_32x32x16_bf16 v[32:47], v[162:165], v[176:179], v[32:47]
	ds_write_b128 v88, v[150:153] offset:36864
	v_mfma_f32_32x32x16_bf16 v[16:31], v[172:175], v[166:169], v[16:31]
	ds_write_b128 v88, v[154:157] offset:40960
	v_mfma_f32_32x32x16_bf16 v[0:15], v[172:175], v[176:179], v[0:15]
	ds_write_b128 v88, v[158:161] offset:45056
	s_waitcnt lgkmcnt(0)
	s_barrier
	ds_read_b128 v[162:165], v95
	ds_read_b128 v[166:169], v96 offset:32768
	ds_read_b128 v[172:175], v95 offset:4096
	ds_read_b128 v[176:179], v96 offset:36864
	v_mfma_f32_32x32x16_bf16 v[48:63], v[188:191], v[192:195], v[48:63]
	global_load_dwordx4 v[138:141], v[66:67], off offset:768
	v_mfma_f32_32x32x16_bf16 v[32:47], v[188:191], v[200:203], v[32:47]
	global_load_dwordx4 v[130:133], v[70:71], off offset:768
	v_mfma_f32_32x32x16_bf16 v[16:31], v[196:199], v[192:195], v[16:31]
	global_load_dwordx4 v[134:137], v[72:73], off offset:768
	v_mfma_f32_32x32x16_bf16 v[0:15], v[196:199], v[200:203], v[0:15]
	global_load_dwordx4 v[146:149], v[74:75], off offset:768
	ds_read_b128 v[188:191], v94
	ds_read_b128 v[192:195], v93 offset:32768
	ds_read_b128 v[196:199], v94 offset:4096
	ds_read_b128 v[200:203], v93 offset:36864
	s_waitcnt lgkmcnt(4)
	v_mfma_f32_32x32x16_bf16 v[48:63], v[162:165], v[166:169], v[48:63]
	global_load_dwordx4 v[142:145], v[68:69], off offset:768
	v_mfma_f32_32x32x16_bf16 v[32:47], v[162:165], v[176:179], v[32:47]
	global_load_dwordx4 v[150:153], v[76:77], off offset:768
	v_mfma_f32_32x32x16_bf16 v[16:31], v[172:175], v[166:169], v[16:31]
	global_load_dwordx4 v[154:157], v[78:79], off offset:768
	v_mfma_f32_32x32x16_bf16 v[0:15], v[172:175], v[176:179], v[0:15]
	global_load_dwordx4 v[158:161], v[82:83], off offset:768
	ds_read_b128 v[162:165], v92
	ds_read_b128 v[166:169], v91 offset:32768
	ds_read_b128 v[172:175], v92 offset:4096
	ds_read_b128 v[176:179], v91 offset:36864
	s_waitcnt lgkmcnt(4)
	s_waitcnt vmcnt(8)
	v_mfma_f32_32x32x16_bf16 v[48:63], v[188:191], v[192:195], v[48:63]
	ds_write_b128 v88, v[98:101] offset:16384
	v_mfma_f32_32x32x16_bf16 v[32:47], v[188:191], v[200:203], v[32:47]
	ds_write_b128 v88, v[106:109] offset:20480
	v_mfma_f32_32x32x16_bf16 v[16:31], v[196:199], v[192:195], v[16:31]
	ds_write_b128 v88, v[110:113] offset:24576
	v_mfma_f32_32x32x16_bf16 v[0:15], v[196:199], v[200:203], v[0:15]
	ds_write_b128 v88, v[114:117] offset:28672
	ds_read_b128 v[188:191], v90
	ds_read_b128 v[192:195], v89 offset:32768
	ds_read_b128 v[196:199], v90 offset:4096
	ds_read_b128 v[200:203], v89 offset:36864
	s_waitcnt lgkmcnt(8)
	v_mfma_f32_32x32x16_bf16 v[48:63], v[162:165], v[166:169], v[48:63]
	ds_write_b128 v88, v[102:105] offset:49152
	v_mfma_f32_32x32x16_bf16 v[32:47], v[162:165], v[176:179], v[32:47]
	ds_write_b128 v88, v[118:121] offset:53248
	v_mfma_f32_32x32x16_bf16 v[16:31], v[172:175], v[166:169], v[16:31]
	ds_write_b128 v88, v[122:125] offset:57344
	v_mfma_f32_32x32x16_bf16 v[0:15], v[172:175], v[176:179], v[0:15]
	ds_write_b128 v88, v[126:129] offset:61440
	s_waitcnt lgkmcnt(0)
	s_barrier
	ds_read_b128 v[162:165], v95 offset:16384
	ds_read_b128 v[166:169], v96 offset:49152
	ds_read_b128 v[172:175], v95 offset:20480
	ds_read_b128 v[176:179], v96 offset:53248
	v_mfma_f32_32x32x16_bf16 v[48:63], v[188:191], v[192:195], v[48:63]
	global_load_dwordx4 v[98:101], v[66:67], off offset:896
	v_mfma_f32_32x32x16_bf16 v[32:47], v[188:191], v[200:203], v[32:47]
	global_load_dwordx4 v[106:109], v[70:71], off offset:896
	v_mfma_f32_32x32x16_bf16 v[16:31], v[196:199], v[192:195], v[16:31]
	global_load_dwordx4 v[110:113], v[72:73], off offset:896
	v_mfma_f32_32x32x16_bf16 v[0:15], v[196:199], v[200:203], v[0:15]
	global_load_dwordx4 v[114:117], v[74:75], off offset:896
	ds_read_b128 v[188:191], v94 offset:16384
	ds_read_b128 v[192:195], v93 offset:49152
	ds_read_b128 v[196:199], v94 offset:20480
	ds_read_b128 v[200:203], v93 offset:53248
	s_waitcnt lgkmcnt(4)
	v_mfma_f32_32x32x16_bf16 v[48:63], v[162:165], v[166:169], v[48:63]
	global_load_dwordx4 v[102:105], v[68:69], off offset:896
	v_mfma_f32_32x32x16_bf16 v[32:47], v[162:165], v[176:179], v[32:47]
	global_load_dwordx4 v[118:121], v[76:77], off offset:896
	v_mfma_f32_32x32x16_bf16 v[16:31], v[172:175], v[166:169], v[16:31]
	global_load_dwordx4 v[122:125], v[78:79], off offset:896
	v_mfma_f32_32x32x16_bf16 v[0:15], v[172:175], v[176:179], v[0:15]
	global_load_dwordx4 v[126:129], v[82:83], off offset:896
	ds_read_b128 v[162:165], v92 offset:16384
	ds_read_b128 v[166:169], v91 offset:49152
	ds_read_b128 v[172:175], v92 offset:20480
	ds_read_b128 v[176:179], v91 offset:53248
	s_waitcnt lgkmcnt(4)
	s_waitcnt vmcnt(8)
	v_mfma_f32_32x32x16_bf16 v[48:63], v[188:191], v[192:195], v[48:63]
	ds_write_b128 v88, v[138:141]
	v_mfma_f32_32x32x16_bf16 v[32:47], v[188:191], v[200:203], v[32:47]
	ds_write_b128 v88, v[130:133] offset:4096
	v_mfma_f32_32x32x16_bf16 v[16:31], v[196:199], v[192:195], v[16:31]
	ds_write_b128 v88, v[134:137] offset:8192
	v_mfma_f32_32x32x16_bf16 v[0:15], v[196:199], v[200:203], v[0:15]
	ds_write_b128 v88, v[146:149] offset:12288
	ds_read_b128 v[188:191], v90 offset:16384
	ds_read_b128 v[192:195], v89 offset:49152
	ds_read_b128 v[196:199], v90 offset:20480
	ds_read_b128 v[200:203], v89 offset:53248
	s_waitcnt lgkmcnt(8)
	v_mfma_f32_32x32x16_bf16 v[48:63], v[162:165], v[166:169], v[48:63]
	ds_write_b128 v88, v[142:145] offset:32768
	v_mfma_f32_32x32x16_bf16 v[32:47], v[162:165], v[176:179], v[32:47]
	ds_write_b128 v88, v[150:153] offset:36864
	v_mfma_f32_32x32x16_bf16 v[16:31], v[172:175], v[166:169], v[16:31]
	ds_write_b128 v88, v[154:157] offset:40960
	v_mfma_f32_32x32x16_bf16 v[0:15], v[172:175], v[176:179], v[0:15]
	ds_write_b128 v88, v[158:161] offset:45056
	s_waitcnt lgkmcnt(0)
	s_barrier
	ds_read_b128 v[162:165], v95
	ds_read_b128 v[166:169], v96 offset:32768
	ds_read_b128 v[172:175], v95 offset:4096
	ds_read_b128 v[176:179], v96 offset:36864
	v_mfma_f32_32x32x16_bf16 v[48:63], v[188:191], v[192:195], v[48:63]
	global_load_dwordx4 v[138:141], v[66:67], off offset:1024
	v_mfma_f32_32x32x16_bf16 v[32:47], v[188:191], v[200:203], v[32:47]
	global_load_dwordx4 v[130:133], v[70:71], off offset:1024
	v_mfma_f32_32x32x16_bf16 v[16:31], v[196:199], v[192:195], v[16:31]
	global_load_dwordx4 v[134:137], v[72:73], off offset:1024
	v_mfma_f32_32x32x16_bf16 v[0:15], v[196:199], v[200:203], v[0:15]
	global_load_dwordx4 v[146:149], v[74:75], off offset:1024
	ds_read_b128 v[188:191], v94
	ds_read_b128 v[192:195], v93 offset:32768
	ds_read_b128 v[196:199], v94 offset:4096
	ds_read_b128 v[200:203], v93 offset:36864
	s_waitcnt lgkmcnt(4)
	v_mfma_f32_32x32x16_bf16 v[48:63], v[162:165], v[166:169], v[48:63]
	global_load_dwordx4 v[142:145], v[68:69], off offset:1024
	v_mfma_f32_32x32x16_bf16 v[32:47], v[162:165], v[176:179], v[32:47]
	global_load_dwordx4 v[150:153], v[76:77], off offset:1024
	v_mfma_f32_32x32x16_bf16 v[16:31], v[172:175], v[166:169], v[16:31]
	global_load_dwordx4 v[154:157], v[78:79], off offset:1024
	v_mfma_f32_32x32x16_bf16 v[0:15], v[172:175], v[176:179], v[0:15]
	global_load_dwordx4 v[158:161], v[82:83], off offset:1024
	ds_read_b128 v[162:165], v92
	ds_read_b128 v[166:169], v91 offset:32768
	ds_read_b128 v[172:175], v92 offset:4096
	ds_read_b128 v[176:179], v91 offset:36864
	s_waitcnt lgkmcnt(4)
	s_waitcnt vmcnt(8)
	v_mfma_f32_32x32x16_bf16 v[48:63], v[188:191], v[192:195], v[48:63]
	ds_write_b128 v88, v[98:101] offset:16384
	v_mfma_f32_32x32x16_bf16 v[32:47], v[188:191], v[200:203], v[32:47]
	ds_write_b128 v88, v[106:109] offset:20480
	v_mfma_f32_32x32x16_bf16 v[16:31], v[196:199], v[192:195], v[16:31]
	ds_write_b128 v88, v[110:113] offset:24576
	v_mfma_f32_32x32x16_bf16 v[0:15], v[196:199], v[200:203], v[0:15]
	ds_write_b128 v88, v[114:117] offset:28672
	ds_read_b128 v[188:191], v90
	ds_read_b128 v[192:195], v89 offset:32768
	ds_read_b128 v[196:199], v90 offset:4096
	ds_read_b128 v[200:203], v89 offset:36864
	s_waitcnt lgkmcnt(8)
	v_mfma_f32_32x32x16_bf16 v[48:63], v[162:165], v[166:169], v[48:63]
	ds_write_b128 v88, v[102:105] offset:49152
	v_mfma_f32_32x32x16_bf16 v[32:47], v[162:165], v[176:179], v[32:47]
	ds_write_b128 v88, v[118:121] offset:53248
	v_mfma_f32_32x32x16_bf16 v[16:31], v[172:175], v[166:169], v[16:31]
	ds_write_b128 v88, v[122:125] offset:57344
	v_mfma_f32_32x32x16_bf16 v[0:15], v[172:175], v[176:179], v[0:15]
	ds_write_b128 v88, v[126:129] offset:61440
	s_waitcnt lgkmcnt(0)
	s_barrier
	ds_read_b128 v[162:165], v95 offset:16384
	ds_read_b128 v[166:169], v96 offset:49152
	ds_read_b128 v[172:175], v95 offset:20480
	ds_read_b128 v[176:179], v96 offset:53248
	v_mfma_f32_32x32x16_bf16 v[48:63], v[188:191], v[192:195], v[48:63]
	global_load_dwordx4 v[98:101], v[66:67], off offset:1152
	v_mfma_f32_32x32x16_bf16 v[32:47], v[188:191], v[200:203], v[32:47]
	global_load_dwordx4 v[106:109], v[70:71], off offset:1152
	v_mfma_f32_32x32x16_bf16 v[16:31], v[196:199], v[192:195], v[16:31]
	global_load_dwordx4 v[110:113], v[72:73], off offset:1152
	v_mfma_f32_32x32x16_bf16 v[0:15], v[196:199], v[200:203], v[0:15]
	global_load_dwordx4 v[114:117], v[74:75], off offset:1152
	ds_read_b128 v[188:191], v94 offset:16384
	ds_read_b128 v[192:195], v93 offset:49152
	ds_read_b128 v[196:199], v94 offset:20480
	ds_read_b128 v[200:203], v93 offset:53248
	s_waitcnt lgkmcnt(4)
	v_mfma_f32_32x32x16_bf16 v[48:63], v[162:165], v[166:169], v[48:63]
	global_load_dwordx4 v[102:105], v[68:69], off offset:1152
	v_mfma_f32_32x32x16_bf16 v[32:47], v[162:165], v[176:179], v[32:47]
	global_load_dwordx4 v[118:121], v[76:77], off offset:1152
	v_mfma_f32_32x32x16_bf16 v[16:31], v[172:175], v[166:169], v[16:31]
	global_load_dwordx4 v[122:125], v[78:79], off offset:1152
	v_mfma_f32_32x32x16_bf16 v[0:15], v[172:175], v[176:179], v[0:15]
	global_load_dwordx4 v[126:129], v[82:83], off offset:1152
	ds_read_b128 v[162:165], v92 offset:16384
	ds_read_b128 v[166:169], v91 offset:49152
	ds_read_b128 v[172:175], v92 offset:20480
	ds_read_b128 v[176:179], v91 offset:53248
	s_waitcnt lgkmcnt(4)
	s_waitcnt vmcnt(8)
	v_mfma_f32_32x32x16_bf16 v[48:63], v[188:191], v[192:195], v[48:63]
	ds_write_b128 v88, v[138:141]
	v_mfma_f32_32x32x16_bf16 v[32:47], v[188:191], v[200:203], v[32:47]
	ds_write_b128 v88, v[130:133] offset:4096
	v_mfma_f32_32x32x16_bf16 v[16:31], v[196:199], v[192:195], v[16:31]
	ds_write_b128 v88, v[134:137] offset:8192
	v_mfma_f32_32x32x16_bf16 v[0:15], v[196:199], v[200:203], v[0:15]
	ds_write_b128 v88, v[146:149] offset:12288
	ds_read_b128 v[188:191], v90 offset:16384
	ds_read_b128 v[192:195], v89 offset:49152
	ds_read_b128 v[196:199], v90 offset:20480
	ds_read_b128 v[200:203], v89 offset:53248
	s_waitcnt lgkmcnt(8)
	v_mfma_f32_32x32x16_bf16 v[48:63], v[162:165], v[166:169], v[48:63]
	ds_write_b128 v88, v[142:145] offset:32768
	v_mfma_f32_32x32x16_bf16 v[32:47], v[162:165], v[176:179], v[32:47]
	ds_write_b128 v88, v[150:153] offset:36864
	v_mfma_f32_32x32x16_bf16 v[16:31], v[172:175], v[166:169], v[16:31]
	ds_write_b128 v88, v[154:157] offset:40960
	v_mfma_f32_32x32x16_bf16 v[0:15], v[172:175], v[176:179], v[0:15]
	ds_write_b128 v88, v[158:161] offset:45056
	s_waitcnt lgkmcnt(0)
	s_barrier
	ds_read_b128 v[162:165], v95
	ds_read_b128 v[166:169], v96 offset:32768
	ds_read_b128 v[172:175], v95 offset:4096
	ds_read_b128 v[176:179], v96 offset:36864
	v_mfma_f32_32x32x16_bf16 v[48:63], v[188:191], v[192:195], v[48:63]
	global_load_dwordx4 v[138:141], v[66:67], off offset:1280
	v_mfma_f32_32x32x16_bf16 v[32:47], v[188:191], v[200:203], v[32:47]
	global_load_dwordx4 v[130:133], v[70:71], off offset:1280
	v_mfma_f32_32x32x16_bf16 v[16:31], v[196:199], v[192:195], v[16:31]
	global_load_dwordx4 v[134:137], v[72:73], off offset:1280
	v_mfma_f32_32x32x16_bf16 v[0:15], v[196:199], v[200:203], v[0:15]
	global_load_dwordx4 v[146:149], v[74:75], off offset:1280
	ds_read_b128 v[188:191], v94
	ds_read_b128 v[192:195], v93 offset:32768
	ds_read_b128 v[196:199], v94 offset:4096
	ds_read_b128 v[200:203], v93 offset:36864
	s_waitcnt lgkmcnt(4)
	v_mfma_f32_32x32x16_bf16 v[48:63], v[162:165], v[166:169], v[48:63]
	global_load_dwordx4 v[142:145], v[68:69], off offset:1280
	v_mfma_f32_32x32x16_bf16 v[32:47], v[162:165], v[176:179], v[32:47]
	global_load_dwordx4 v[150:153], v[76:77], off offset:1280
	v_mfma_f32_32x32x16_bf16 v[16:31], v[172:175], v[166:169], v[16:31]
	global_load_dwordx4 v[154:157], v[78:79], off offset:1280
	v_mfma_f32_32x32x16_bf16 v[0:15], v[172:175], v[176:179], v[0:15]
	global_load_dwordx4 v[158:161], v[82:83], off offset:1280
	ds_read_b128 v[162:165], v92
	ds_read_b128 v[166:169], v91 offset:32768
	ds_read_b128 v[172:175], v92 offset:4096
	ds_read_b128 v[176:179], v91 offset:36864
	s_waitcnt lgkmcnt(4)
	s_waitcnt vmcnt(8)
	v_mfma_f32_32x32x16_bf16 v[48:63], v[188:191], v[192:195], v[48:63]
	ds_write_b128 v88, v[98:101] offset:16384
	v_mfma_f32_32x32x16_bf16 v[32:47], v[188:191], v[200:203], v[32:47]
	ds_write_b128 v88, v[106:109] offset:20480
	v_mfma_f32_32x32x16_bf16 v[16:31], v[196:199], v[192:195], v[16:31]
	ds_write_b128 v88, v[110:113] offset:24576
	v_mfma_f32_32x32x16_bf16 v[0:15], v[196:199], v[200:203], v[0:15]
	ds_write_b128 v88, v[114:117] offset:28672
	ds_read_b128 v[188:191], v90
	ds_read_b128 v[192:195], v89 offset:32768
	ds_read_b128 v[196:199], v90 offset:4096
	ds_read_b128 v[200:203], v89 offset:36864
	s_waitcnt lgkmcnt(8)
	v_mfma_f32_32x32x16_bf16 v[48:63], v[162:165], v[166:169], v[48:63]
	ds_write_b128 v88, v[102:105] offset:49152
	v_mfma_f32_32x32x16_bf16 v[32:47], v[162:165], v[176:179], v[32:47]
	ds_write_b128 v88, v[118:121] offset:53248
	v_mfma_f32_32x32x16_bf16 v[16:31], v[172:175], v[166:169], v[16:31]
	ds_write_b128 v88, v[122:125] offset:57344
	v_mfma_f32_32x32x16_bf16 v[0:15], v[172:175], v[176:179], v[0:15]
	ds_write_b128 v88, v[126:129] offset:61440
	s_waitcnt lgkmcnt(0)
	s_barrier
	ds_read_b128 v[162:165], v95 offset:16384
	ds_read_b128 v[166:169], v96 offset:49152
	ds_read_b128 v[172:175], v95 offset:20480
	ds_read_b128 v[176:179], v96 offset:53248
	v_mfma_f32_32x32x16_bf16 v[48:63], v[188:191], v[192:195], v[48:63]
	global_load_dwordx4 v[98:101], v[66:67], off offset:1408
	v_mfma_f32_32x32x16_bf16 v[32:47], v[188:191], v[200:203], v[32:47]
	global_load_dwordx4 v[106:109], v[70:71], off offset:1408
	v_mfma_f32_32x32x16_bf16 v[16:31], v[196:199], v[192:195], v[16:31]
	global_load_dwordx4 v[110:113], v[72:73], off offset:1408
	v_mfma_f32_32x32x16_bf16 v[0:15], v[196:199], v[200:203], v[0:15]
	global_load_dwordx4 v[114:117], v[74:75], off offset:1408
	ds_read_b128 v[188:191], v94 offset:16384
	ds_read_b128 v[192:195], v93 offset:49152
	ds_read_b128 v[196:199], v94 offset:20480
	ds_read_b128 v[200:203], v93 offset:53248
	s_waitcnt lgkmcnt(4)
	v_mfma_f32_32x32x16_bf16 v[48:63], v[162:165], v[166:169], v[48:63]
	global_load_dwordx4 v[102:105], v[68:69], off offset:1408
	v_mfma_f32_32x32x16_bf16 v[32:47], v[162:165], v[176:179], v[32:47]
	global_load_dwordx4 v[118:121], v[76:77], off offset:1408
	v_mfma_f32_32x32x16_bf16 v[16:31], v[172:175], v[166:169], v[16:31]
	global_load_dwordx4 v[122:125], v[78:79], off offset:1408
	v_mfma_f32_32x32x16_bf16 v[0:15], v[172:175], v[176:179], v[0:15]
	global_load_dwordx4 v[126:129], v[82:83], off offset:1408
	ds_read_b128 v[162:165], v92 offset:16384
	ds_read_b128 v[166:169], v91 offset:49152
	ds_read_b128 v[172:175], v92 offset:20480
	ds_read_b128 v[176:179], v91 offset:53248
	s_waitcnt lgkmcnt(4)
	s_waitcnt vmcnt(8)
	v_mfma_f32_32x32x16_bf16 v[48:63], v[188:191], v[192:195], v[48:63]
	ds_write_b128 v88, v[138:141]
	v_mfma_f32_32x32x16_bf16 v[32:47], v[188:191], v[200:203], v[32:47]
	ds_write_b128 v88, v[130:133] offset:4096
	v_mfma_f32_32x32x16_bf16 v[16:31], v[196:199], v[192:195], v[16:31]
	ds_write_b128 v88, v[134:137] offset:8192
	v_mfma_f32_32x32x16_bf16 v[0:15], v[196:199], v[200:203], v[0:15]
	ds_write_b128 v88, v[146:149] offset:12288
	ds_read_b128 v[188:191], v90 offset:16384
	ds_read_b128 v[192:195], v89 offset:49152
	ds_read_b128 v[196:199], v90 offset:20480
	ds_read_b128 v[200:203], v89 offset:53248
	s_waitcnt lgkmcnt(8)
	v_mfma_f32_32x32x16_bf16 v[48:63], v[162:165], v[166:169], v[48:63]
	ds_write_b128 v88, v[142:145] offset:32768
	v_mfma_f32_32x32x16_bf16 v[32:47], v[162:165], v[176:179], v[32:47]
	ds_write_b128 v88, v[150:153] offset:36864
	v_mfma_f32_32x32x16_bf16 v[16:31], v[172:175], v[166:169], v[16:31]
	ds_write_b128 v88, v[154:157] offset:40960
	v_mfma_f32_32x32x16_bf16 v[0:15], v[172:175], v[176:179], v[0:15]
	ds_write_b128 v88, v[158:161] offset:45056
	s_waitcnt lgkmcnt(0)
	s_barrier
	ds_read_b128 v[162:165], v95
	ds_read_b128 v[166:169], v96 offset:32768
	ds_read_b128 v[172:175], v95 offset:4096
	ds_read_b128 v[176:179], v96 offset:36864
	v_mfma_f32_32x32x16_bf16 v[48:63], v[188:191], v[192:195], v[48:63]
	global_load_dwordx4 v[138:141], v[66:67], off offset:1536
	v_mfma_f32_32x32x16_bf16 v[32:47], v[188:191], v[200:203], v[32:47]
	global_load_dwordx4 v[130:133], v[70:71], off offset:1536
	v_mfma_f32_32x32x16_bf16 v[16:31], v[196:199], v[192:195], v[16:31]
	global_load_dwordx4 v[134:137], v[72:73], off offset:1536
	v_mfma_f32_32x32x16_bf16 v[0:15], v[196:199], v[200:203], v[0:15]
	global_load_dwordx4 v[146:149], v[74:75], off offset:1536
	ds_read_b128 v[188:191], v94
	ds_read_b128 v[192:195], v93 offset:32768
	ds_read_b128 v[196:199], v94 offset:4096
	ds_read_b128 v[200:203], v93 offset:36864
	s_waitcnt lgkmcnt(4)
	v_mfma_f32_32x32x16_bf16 v[48:63], v[162:165], v[166:169], v[48:63]
	global_load_dwordx4 v[142:145], v[68:69], off offset:1536
	v_mfma_f32_32x32x16_bf16 v[32:47], v[162:165], v[176:179], v[32:47]
	global_load_dwordx4 v[150:153], v[76:77], off offset:1536
	v_mfma_f32_32x32x16_bf16 v[16:31], v[172:175], v[166:169], v[16:31]
	global_load_dwordx4 v[154:157], v[78:79], off offset:1536
	v_mfma_f32_32x32x16_bf16 v[0:15], v[172:175], v[176:179], v[0:15]
	global_load_dwordx4 v[158:161], v[82:83], off offset:1536
	ds_read_b128 v[162:165], v92
	ds_read_b128 v[166:169], v91 offset:32768
	ds_read_b128 v[172:175], v92 offset:4096
	ds_read_b128 v[176:179], v91 offset:36864
	s_waitcnt lgkmcnt(4)
	s_waitcnt vmcnt(8)
	v_mfma_f32_32x32x16_bf16 v[48:63], v[188:191], v[192:195], v[48:63]
	ds_write_b128 v88, v[98:101] offset:16384
	v_mfma_f32_32x32x16_bf16 v[32:47], v[188:191], v[200:203], v[32:47]
	ds_write_b128 v88, v[106:109] offset:20480
	v_mfma_f32_32x32x16_bf16 v[16:31], v[196:199], v[192:195], v[16:31]
	ds_write_b128 v88, v[110:113] offset:24576
	v_mfma_f32_32x32x16_bf16 v[0:15], v[196:199], v[200:203], v[0:15]
	ds_write_b128 v88, v[114:117] offset:28672
	ds_read_b128 v[188:191], v90
	ds_read_b128 v[192:195], v89 offset:32768
	ds_read_b128 v[196:199], v90 offset:4096
	ds_read_b128 v[200:203], v89 offset:36864
	s_waitcnt lgkmcnt(8)
	v_mfma_f32_32x32x16_bf16 v[48:63], v[162:165], v[166:169], v[48:63]
	ds_write_b128 v88, v[102:105] offset:49152
	v_mfma_f32_32x32x16_bf16 v[32:47], v[162:165], v[176:179], v[32:47]
	ds_write_b128 v88, v[118:121] offset:53248
	v_mfma_f32_32x32x16_bf16 v[16:31], v[172:175], v[166:169], v[16:31]
	ds_write_b128 v88, v[122:125] offset:57344
	v_mfma_f32_32x32x16_bf16 v[0:15], v[172:175], v[176:179], v[0:15]
	ds_write_b128 v88, v[126:129] offset:61440
	s_waitcnt lgkmcnt(0)
	s_barrier
	ds_read_b128 v[162:165], v95 offset:16384
	ds_read_b128 v[166:169], v96 offset:49152
	ds_read_b128 v[172:175], v95 offset:20480
	ds_read_b128 v[176:179], v96 offset:53248
	v_mfma_f32_32x32x16_bf16 v[48:63], v[188:191], v[192:195], v[48:63]
	global_load_dwordx4 v[98:101], v[66:67], off offset:1664
	v_mfma_f32_32x32x16_bf16 v[32:47], v[188:191], v[200:203], v[32:47]
	global_load_dwordx4 v[106:109], v[70:71], off offset:1664
	v_mfma_f32_32x32x16_bf16 v[16:31], v[196:199], v[192:195], v[16:31]
	global_load_dwordx4 v[110:113], v[72:73], off offset:1664
	v_mfma_f32_32x32x16_bf16 v[0:15], v[196:199], v[200:203], v[0:15]
	global_load_dwordx4 v[114:117], v[74:75], off offset:1664
	ds_read_b128 v[188:191], v94 offset:16384
	ds_read_b128 v[192:195], v93 offset:49152
	ds_read_b128 v[196:199], v94 offset:20480
	ds_read_b128 v[200:203], v93 offset:53248
	s_waitcnt lgkmcnt(4)
	v_mfma_f32_32x32x16_bf16 v[48:63], v[162:165], v[166:169], v[48:63]
	global_load_dwordx4 v[102:105], v[68:69], off offset:1664
	v_mfma_f32_32x32x16_bf16 v[32:47], v[162:165], v[176:179], v[32:47]
	global_load_dwordx4 v[118:121], v[76:77], off offset:1664
	v_mfma_f32_32x32x16_bf16 v[16:31], v[172:175], v[166:169], v[16:31]
	global_load_dwordx4 v[122:125], v[78:79], off offset:1664
	v_mfma_f32_32x32x16_bf16 v[0:15], v[172:175], v[176:179], v[0:15]
	global_load_dwordx4 v[126:129], v[82:83], off offset:1664
	ds_read_b128 v[162:165], v92 offset:16384
	ds_read_b128 v[166:169], v91 offset:49152
	ds_read_b128 v[172:175], v92 offset:20480
	ds_read_b128 v[176:179], v91 offset:53248
	s_waitcnt lgkmcnt(4)
	s_waitcnt vmcnt(8)
	v_mfma_f32_32x32x16_bf16 v[48:63], v[188:191], v[192:195], v[48:63]
	ds_write_b128 v88, v[138:141]
	v_mfma_f32_32x32x16_bf16 v[32:47], v[188:191], v[200:203], v[32:47]
	ds_write_b128 v88, v[130:133] offset:4096
	v_mfma_f32_32x32x16_bf16 v[16:31], v[196:199], v[192:195], v[16:31]
	ds_write_b128 v88, v[134:137] offset:8192
	v_mfma_f32_32x32x16_bf16 v[0:15], v[196:199], v[200:203], v[0:15]
	ds_write_b128 v88, v[146:149] offset:12288
	ds_read_b128 v[188:191], v90 offset:16384
	ds_read_b128 v[192:195], v89 offset:49152
	ds_read_b128 v[196:199], v90 offset:20480
	ds_read_b128 v[200:203], v89 offset:53248
	s_waitcnt lgkmcnt(8)
	v_mfma_f32_32x32x16_bf16 v[48:63], v[162:165], v[166:169], v[48:63]
	ds_write_b128 v88, v[142:145] offset:32768
	v_mfma_f32_32x32x16_bf16 v[32:47], v[162:165], v[176:179], v[32:47]
	ds_write_b128 v88, v[150:153] offset:36864
	v_mfma_f32_32x32x16_bf16 v[16:31], v[172:175], v[166:169], v[16:31]
	ds_write_b128 v88, v[154:157] offset:40960
	v_mfma_f32_32x32x16_bf16 v[0:15], v[172:175], v[176:179], v[0:15]
	ds_write_b128 v88, v[158:161] offset:45056
	s_waitcnt lgkmcnt(0)
	s_barrier
	ds_read_b128 v[162:165], v95
	ds_read_b128 v[166:169], v96 offset:32768
	ds_read_b128 v[172:175], v95 offset:4096
	ds_read_b128 v[176:179], v96 offset:36864
	v_mfma_f32_32x32x16_bf16 v[48:63], v[188:191], v[192:195], v[48:63]
	global_load_dwordx4 v[138:141], v[66:67], off offset:1792
	v_mfma_f32_32x32x16_bf16 v[32:47], v[188:191], v[200:203], v[32:47]
	global_load_dwordx4 v[130:133], v[70:71], off offset:1792
	v_mfma_f32_32x32x16_bf16 v[16:31], v[196:199], v[192:195], v[16:31]
	global_load_dwordx4 v[134:137], v[72:73], off offset:1792
	v_mfma_f32_32x32x16_bf16 v[0:15], v[196:199], v[200:203], v[0:15]
	global_load_dwordx4 v[146:149], v[74:75], off offset:1792
	ds_read_b128 v[188:191], v94
	ds_read_b128 v[192:195], v93 offset:32768
	ds_read_b128 v[196:199], v94 offset:4096
	ds_read_b128 v[200:203], v93 offset:36864
	s_waitcnt lgkmcnt(4)
	v_mfma_f32_32x32x16_bf16 v[48:63], v[162:165], v[166:169], v[48:63]
	global_load_dwordx4 v[142:145], v[68:69], off offset:1792
	v_mfma_f32_32x32x16_bf16 v[32:47], v[162:165], v[176:179], v[32:47]
	global_load_dwordx4 v[150:153], v[76:77], off offset:1792
	v_mfma_f32_32x32x16_bf16 v[16:31], v[172:175], v[166:169], v[16:31]
	global_load_dwordx4 v[154:157], v[78:79], off offset:1792
	v_mfma_f32_32x32x16_bf16 v[0:15], v[172:175], v[176:179], v[0:15]
	global_load_dwordx4 v[158:161], v[82:83], off offset:1792
	ds_read_b128 v[162:165], v92
	ds_read_b128 v[166:169], v91 offset:32768
	ds_read_b128 v[172:175], v92 offset:4096
	ds_read_b128 v[176:179], v91 offset:36864
	s_waitcnt lgkmcnt(4)
	s_waitcnt vmcnt(8)
	v_mfma_f32_32x32x16_bf16 v[48:63], v[188:191], v[192:195], v[48:63]
	ds_write_b128 v88, v[98:101] offset:16384
	v_mfma_f32_32x32x16_bf16 v[32:47], v[188:191], v[200:203], v[32:47]
	ds_write_b128 v88, v[106:109] offset:20480
	v_mfma_f32_32x32x16_bf16 v[16:31], v[196:199], v[192:195], v[16:31]
	ds_write_b128 v88, v[110:113] offset:24576
	v_mfma_f32_32x32x16_bf16 v[0:15], v[196:199], v[200:203], v[0:15]
	ds_write_b128 v88, v[114:117] offset:28672
	ds_read_b128 v[188:191], v90
	ds_read_b128 v[192:195], v89 offset:32768
	ds_read_b128 v[196:199], v90 offset:4096
	ds_read_b128 v[200:203], v89 offset:36864
	s_waitcnt lgkmcnt(8)
	v_mfma_f32_32x32x16_bf16 v[48:63], v[162:165], v[166:169], v[48:63]
	ds_write_b128 v88, v[102:105] offset:49152
	v_mfma_f32_32x32x16_bf16 v[32:47], v[162:165], v[176:179], v[32:47]
	ds_write_b128 v88, v[118:121] offset:53248
	v_mfma_f32_32x32x16_bf16 v[16:31], v[172:175], v[166:169], v[16:31]
	ds_write_b128 v88, v[122:125] offset:57344
	v_mfma_f32_32x32x16_bf16 v[0:15], v[172:175], v[176:179], v[0:15]
	ds_write_b128 v88, v[126:129] offset:61440
	s_waitcnt lgkmcnt(0)
	s_barrier
	ds_read_b128 v[162:165], v95 offset:16384
	ds_read_b128 v[166:169], v96 offset:49152
	ds_read_b128 v[172:175], v95 offset:20480
	ds_read_b128 v[176:179], v96 offset:53248
	v_mfma_f32_32x32x16_bf16 v[48:63], v[188:191], v[192:195], v[48:63]
	global_load_dwordx4 v[98:101], v[66:67], off offset:1920
	v_mfma_f32_32x32x16_bf16 v[32:47], v[188:191], v[200:203], v[32:47]
	global_load_dwordx4 v[106:109], v[70:71], off offset:1920
	v_mfma_f32_32x32x16_bf16 v[16:31], v[196:199], v[192:195], v[16:31]
	global_load_dwordx4 v[110:113], v[72:73], off offset:1920
	v_mfma_f32_32x32x16_bf16 v[0:15], v[196:199], v[200:203], v[0:15]
	global_load_dwordx4 v[114:117], v[74:75], off offset:1920
	ds_read_b128 v[188:191], v94 offset:16384
	ds_read_b128 v[192:195], v93 offset:49152
	ds_read_b128 v[196:199], v94 offset:20480
	ds_read_b128 v[200:203], v93 offset:53248
	s_waitcnt lgkmcnt(4)
	v_mfma_f32_32x32x16_bf16 v[48:63], v[162:165], v[166:169], v[48:63]
	global_load_dwordx4 v[102:105], v[68:69], off offset:1920
	v_mfma_f32_32x32x16_bf16 v[32:47], v[162:165], v[176:179], v[32:47]
	global_load_dwordx4 v[118:121], v[76:77], off offset:1920
	v_mfma_f32_32x32x16_bf16 v[16:31], v[172:175], v[166:169], v[16:31]
	global_load_dwordx4 v[122:125], v[78:79], off offset:1920
	v_mfma_f32_32x32x16_bf16 v[0:15], v[172:175], v[176:179], v[0:15]
	global_load_dwordx4 v[126:129], v[82:83], off offset:1920
	ds_read_b128 v[162:165], v92 offset:16384
	ds_read_b128 v[166:169], v91 offset:49152
	ds_read_b128 v[172:175], v92 offset:20480
	ds_read_b128 v[176:179], v91 offset:53248
	s_waitcnt lgkmcnt(4)
	s_waitcnt vmcnt(8)
	v_mfma_f32_32x32x16_bf16 v[48:63], v[188:191], v[192:195], v[48:63]
	ds_write_b128 v88, v[138:141]
	v_mfma_f32_32x32x16_bf16 v[32:47], v[188:191], v[200:203], v[32:47]
	ds_write_b128 v88, v[130:133] offset:4096
	v_mfma_f32_32x32x16_bf16 v[16:31], v[196:199], v[192:195], v[16:31]
	ds_write_b128 v88, v[134:137] offset:8192
	v_mfma_f32_32x32x16_bf16 v[0:15], v[196:199], v[200:203], v[0:15]
	ds_write_b128 v88, v[146:149] offset:12288
	ds_read_b128 v[188:191], v90 offset:16384
	ds_read_b128 v[192:195], v89 offset:49152
	ds_read_b128 v[196:199], v90 offset:20480
	ds_read_b128 v[200:203], v89 offset:53248
	s_waitcnt lgkmcnt(8)
	v_mfma_f32_32x32x16_bf16 v[48:63], v[162:165], v[166:169], v[48:63]
	ds_write_b128 v88, v[142:145] offset:32768
	v_mfma_f32_32x32x16_bf16 v[32:47], v[162:165], v[176:179], v[32:47]
	ds_write_b128 v88, v[150:153] offset:36864
	v_mfma_f32_32x32x16_bf16 v[16:31], v[172:175], v[166:169], v[16:31]
	ds_write_b128 v88, v[154:157] offset:40960
	v_mfma_f32_32x32x16_bf16 v[0:15], v[172:175], v[176:179], v[0:15]
	ds_write_b128 v88, v[158:161] offset:45056
	s_waitcnt lgkmcnt(0)
	s_barrier
	ds_read_b128 v[162:165], v95
	ds_read_b128 v[166:169], v96 offset:32768
	ds_read_b128 v[172:175], v95 offset:4096
	ds_read_b128 v[176:179], v96 offset:36864
	v_mfma_f32_32x32x16_bf16 v[48:63], v[188:191], v[192:195], v[48:63]
	v_mfma_f32_32x32x16_bf16 v[32:47], v[188:191], v[200:203], v[32:47]
	v_mfma_f32_32x32x16_bf16 v[16:31], v[196:199], v[192:195], v[16:31]
	v_mfma_f32_32x32x16_bf16 v[0:15], v[196:199], v[200:203], v[0:15]
	ds_read_b128 v[188:191], v94
	ds_read_b128 v[192:195], v93 offset:32768
	ds_read_b128 v[196:199], v94 offset:4096
	ds_read_b128 v[200:203], v93 offset:36864
	s_waitcnt lgkmcnt(4)
	v_mfma_f32_32x32x16_bf16 v[48:63], v[162:165], v[166:169], v[48:63]
	v_mfma_f32_32x32x16_bf16 v[32:47], v[162:165], v[176:179], v[32:47]
	v_mfma_f32_32x32x16_bf16 v[16:31], v[172:175], v[166:169], v[16:31]
	v_mfma_f32_32x32x16_bf16 v[0:15], v[172:175], v[176:179], v[0:15]
	ds_read_b128 v[162:165], v92
	ds_read_b128 v[166:169], v91 offset:32768
	ds_read_b128 v[172:175], v92 offset:4096
	ds_read_b128 v[176:179], v91 offset:36864
	s_waitcnt lgkmcnt(4)
	s_waitcnt vmcnt(0)
	v_mfma_f32_32x32x16_bf16 v[48:63], v[188:191], v[192:195], v[48:63]
	ds_write_b128 v88, v[98:101] offset:16384
	v_mfma_f32_32x32x16_bf16 v[32:47], v[188:191], v[200:203], v[32:47]
	ds_write_b128 v88, v[106:109] offset:20480
	v_mfma_f32_32x32x16_bf16 v[16:31], v[196:199], v[192:195], v[16:31]
	ds_write_b128 v88, v[110:113] offset:24576
	v_mfma_f32_32x32x16_bf16 v[0:15], v[196:199], v[200:203], v[0:15]
	ds_write_b128 v88, v[114:117] offset:28672
	ds_read_b128 v[188:191], v90
	ds_read_b128 v[192:195], v89 offset:32768
	ds_read_b128 v[196:199], v90 offset:4096
	ds_read_b128 v[200:203], v89 offset:36864
	s_waitcnt lgkmcnt(8)
	v_mfma_f32_32x32x16_bf16 v[48:63], v[162:165], v[166:169], v[48:63]
	ds_write_b128 v88, v[102:105] offset:49152
	v_mfma_f32_32x32x16_bf16 v[32:47], v[162:165], v[176:179], v[32:47]
	ds_write_b128 v88, v[118:121] offset:53248
	v_mfma_f32_32x32x16_bf16 v[16:31], v[172:175], v[166:169], v[16:31]
	ds_write_b128 v88, v[122:125] offset:57344
	v_mfma_f32_32x32x16_bf16 v[0:15], v[172:175], v[176:179], v[0:15]
	ds_write_b128 v88, v[126:129] offset:61440
	s_waitcnt lgkmcnt(0)
	s_barrier
	ds_read_b128 v[162:165], v95 offset:16384
	ds_read_b128 v[166:169], v96 offset:49152
	ds_read_b128 v[172:175], v95 offset:20480
	ds_read_b128 v[176:179], v96 offset:53248
	v_mfma_f32_32x32x16_bf16 v[48:63], v[188:191], v[192:195], v[48:63]
	v_mfma_f32_32x32x16_bf16 v[32:47], v[188:191], v[200:203], v[32:47]
	v_mfma_f32_32x32x16_bf16 v[16:31], v[196:199], v[192:195], v[16:31]
	v_mfma_f32_32x32x16_bf16 v[0:15], v[196:199], v[200:203], v[0:15]
	ds_read_b128 v[188:191], v94 offset:16384
	ds_read_b128 v[192:195], v93 offset:49152
	ds_read_b128 v[196:199], v94 offset:20480
	ds_read_b128 v[200:203], v93 offset:53248
	s_waitcnt lgkmcnt(4)
	v_mfma_f32_32x32x16_bf16 v[48:63], v[162:165], v[166:169], v[48:63]
	v_mfma_f32_32x32x16_bf16 v[32:47], v[162:165], v[176:179], v[32:47]
	v_mfma_f32_32x32x16_bf16 v[16:31], v[172:175], v[166:169], v[16:31]
	v_mfma_f32_32x32x16_bf16 v[0:15], v[172:175], v[176:179], v[0:15]
	ds_read_b128 v[162:165], v92 offset:16384
	ds_read_b128 v[166:169], v91 offset:49152
	ds_read_b128 v[172:175], v92 offset:20480
	ds_read_b128 v[176:179], v91 offset:53248
	s_waitcnt lgkmcnt(4)
	v_mfma_f32_32x32x16_bf16 v[48:63], v[188:191], v[192:195], v[48:63]
	v_mfma_f32_32x32x16_bf16 v[32:47], v[188:191], v[200:203], v[32:47]
	v_mfma_f32_32x32x16_bf16 v[16:31], v[196:199], v[192:195], v[16:31]
	v_mfma_f32_32x32x16_bf16 v[0:15], v[196:199], v[200:203], v[0:15]
	ds_read_b128 v[188:191], v90 offset:16384
	ds_read_b128 v[192:195], v89 offset:49152
	ds_read_b128 v[196:199], v90 offset:20480
	ds_read_b128 v[200:203], v89 offset:53248
	s_waitcnt lgkmcnt(4)
	v_mfma_f32_32x32x16_bf16 v[48:63], v[162:165], v[166:169], v[48:63]
	v_mfma_f32_32x32x16_bf16 v[32:47], v[162:165], v[176:179], v[32:47]
	v_mfma_f32_32x32x16_bf16 v[16:31], v[172:175], v[166:169], v[16:31]
	v_mfma_f32_32x32x16_bf16 v[0:15], v[172:175], v[176:179], v[0:15]
	s_waitcnt lgkmcnt(0)
	s_barrier
	v_mfma_f32_32x32x16_bf16 v[48:63], v[188:191], v[192:195], v[48:63]
	v_mfma_f32_32x32x16_bf16 v[32:47], v[188:191], v[200:203], v[32:47]
	v_mfma_f32_32x32x16_bf16 v[16:31], v[196:199], v[192:195], v[16:31]
	v_mfma_f32_32x32x16_bf16 v[0:15], v[196:199], v[200:203], v[0:15]
	s_nop 15
	s_nop 0
	s_nop 0
	s_nop 0
	s_nop 0
	s_nop 0
	s_nop 0
	v_lshlrev_b32_e32 v72, 2, v86
	s_cmp_eq_u32 s37, 5
	s_cselect_b64 s[6:7], -1, 0
	s_cmp_lg_u32 s37, 5
	v_and_b32_e32 v66, 64, v85
	v_or3_b32 v70, v66, s1, v64
	v_add_u32_e32 v68, s0, v87
	v_readlane_b32 s0, v252, 37
	v_or_b32_e32 v73, v68, v72
	v_ashrrev_i32_e32 v71, 31, v70
	v_readlane_b32 s1, v252, 38
	v_or_b32_e32 v74, 2, v73
	v_lshl_add_u64 v[66:67], v[70:71], 1, s[0:1]
	v_mad_i64_i32 v[82:83], s[0:1], v73, s17, v[66:67]
	v_or_b32_e32 v71, 1, v73
	v_mad_i64_i32 v[78:79], s[0:1], v74, s17, v[66:67]
	v_mad_i64_i32 v[86:87], s[0:1], v71, s17, v[66:67]
	v_ashrrev_i32_e32 v69, 31, v68
	s_nop 10
	v_and_b32_sdwa v64, v49, v84 dst_sel:DWORD dst_unused:UNUSED_PAD src0_sel:WORD_1 src1_sel:DWORD
	v_and_b32_sdwa v75, v48, v84 dst_sel:DWORD dst_unused:UNUSED_PAD src0_sel:WORD_1 src1_sel:DWORD
	v_add3_u32 v49, v49, v64, s18
	v_and_b32_sdwa v64, v50, v84 dst_sel:DWORD dst_unused:UNUSED_PAD src0_sel:WORD_1 src1_sel:DWORD
	v_add3_u32 v75, v48, v75, s18
	v_and_b32_sdwa v48, v51, v84 dst_sel:DWORD dst_unused:UNUSED_PAD src0_sel:WORD_1 src1_sel:DWORD
	v_add3_u32 v76, v50, v64, s18
	v_or_b32_e32 v50, 3, v73
	global_store_short_d16_hi v[82:83], v75, off
	global_store_short_d16_hi v[86:87], v49, off
	v_add3_u32 v77, v51, v48, s18
	global_store_short_d16_hi v[78:79], v76, off
	v_mad_i64_i32 v[78:79], s[0:1], v50, s17, v[66:67]
	v_or_b32_e32 v51, 8, v73
	v_and_b32_sdwa v64, v52, v84 dst_sel:DWORD dst_unused:UNUSED_PAD src0_sel:WORD_1 src1_sel:DWORD
	global_store_short_d16_hi v[78:79], v77, off
	v_mad_i64_i32 v[82:83], s[0:1], v51, s17, v[66:67]
	v_and_b32_sdwa v48, v53, v84 dst_sel:DWORD dst_unused:UNUSED_PAD src0_sel:WORD_1 src1_sel:DWORD
	v_add3_u32 v78, v52, v64, s18
	v_or_b32_e32 v52, 9, v73
	v_add3_u32 v79, v53, v48, s18
	global_store_short_d16_hi v[82:83], v78, off
	v_mad_i64_i32 v[82:83], s[0:1], v52, s17, v[66:67]
	v_or_b32_e32 v53, 10, v73
	v_and_b32_sdwa v48, v55, v84 dst_sel:DWORD dst_unused:UNUSED_PAD src0_sel:WORD_1 src1_sel:DWORD
	v_and_b32_sdwa v64, v54, v84 dst_sel:DWORD dst_unused:UNUSED_PAD src0_sel:WORD_1 src1_sel:DWORD
	global_store_short_d16_hi v[82:83], v79, off
	v_mad_i64_i32 v[86:87], s[0:1], v53, s17, v[66:67]
	v_add3_u32 v82, v54, v64, s18
	v_add3_u32 v83, v55, v48, s18
	v_or_b32_e32 v54, 11, v73
	v_or_b32_e32 v55, 16, v73
	v_and_b32_sdwa v64, v56, v84 dst_sel:DWORD dst_unused:UNUSED_PAD src0_sel:WORD_1 src1_sel:DWORD
	global_store_short_d16_hi v[86:87], v82, off
	v_mad_i64_i32 v[86:87], s[0:1], v54, s17, v[66:67]
	v_mad_i64_i32 v[88:89], s[0:1], v55, s17, v[66:67]
	v_and_b32_sdwa v48, v57, v84 dst_sel:DWORD dst_unused:UNUSED_PAD src0_sel:WORD_1 src1_sel:DWORD
	v_add3_u32 v85, v56, v64, s18
	v_or_b32_e32 v56, 17, v73
	v_and_b32_sdwa v64, v58, v84 dst_sel:DWORD dst_unused:UNUSED_PAD src0_sel:WORD_1 src1_sel:DWORD
	global_store_short_d16_hi v[86:87], v83, off
	v_add3_u32 v86, v57, v48, s18
	global_store_short_d16_hi v[88:89], v85, off
	v_mad_i64_i32 v[88:89], s[0:1], v56, s17, v[66:67]
	v_and_b32_sdwa v48, v59, v84 dst_sel:DWORD dst_unused:UNUSED_PAD src0_sel:WORD_1 src1_sel:DWORD
	v_add3_u32 v87, v58, v64, s18
	v_and_b32_sdwa v64, v60, v84 dst_sel:DWORD dst_unused:UNUSED_PAD src0_sel:WORD_1 src1_sel:DWORD
	global_store_short_d16_hi v[88:89], v86, off
	v_or_b32_e32 v57, 18, v73
	v_add3_u32 v88, v59, v48, s18
	v_and_b32_sdwa v48, v61, v84 dst_sel:DWORD dst_unused:UNUSED_PAD src0_sel:WORD_1 src1_sel:DWORD
	v_add3_u32 v89, v60, v64, s18
	v_or_b32_e32 v60, 25, v73
	v_mad_i64_i32 v[94:95], s[0:1], v57, s17, v[66:67]
	v_or_b32_e32 v58, 19, v73
	v_add3_u32 v90, v61, v48, s18
	v_mad_i64_i32 v[92:93], s[0:1], v60, s17, v[66:67]
	v_or_b32_e32 v61, 26, v73
	v_and_b32_sdwa v64, v62, v84 dst_sel:DWORD dst_unused:UNUSED_PAD src0_sel:WORD_1 src1_sel:DWORD
	global_store_short_d16_hi v[94:95], v87, off
	v_mad_i64_i32 v[94:95], s[0:1], v58, s17, v[66:67]
	v_or_b32_e32 v59, 24, v73
	global_store_short_d16_hi v[92:93], v90, off
	v_mad_i64_i32 v[92:93], s[0:1], v61, s17, v[66:67]
	v_and_b32_sdwa v48, v63, v84 dst_sel:DWORD dst_unused:UNUSED_PAD src0_sel:WORD_1 src1_sel:DWORD
	v_add3_u32 v91, v62, v64, s18
	v_or_b32_e32 v62, 27, v73
	global_store_short_d16_hi v[94:95], v88, off
	v_mad_i64_i32 v[94:95], s[0:1], v59, s17, v[66:67]
	v_add3_u32 v63, v63, v48, s18
	global_store_short_d16_hi v[92:93], v91, off
	v_mad_i64_i32 v[92:93], s[0:1], v62, s17, v[66:67]
	v_mul_lo_u32 v64, v70, s19
	v_lshlrev_b32_e32 v48, 1, v72
	global_store_short_d16_hi v[94:95], v89, off
	global_store_short_d16_hi v[92:93], v63, off
	s_cbranch_scc1 .LBB0_132
	v_readlane_b32 s0, v252, 0
	v_readlane_b32 s1, v252, 1
	v_lshrrev_b32_e32 v93, 16, v77
	v_lshrrev_b32_e32 v94, 16, v76
	v_lshl_add_u64 v[76:77], v[64:65], 1, s[0:1]
	v_lshrrev_b32_e32 v92, 16, v49
	v_lshl_add_u64 v[76:77], v[68:69], 1, v[76:77]
	v_mov_b32_e32 v49, v65
	v_lshl_add_u64 v[76:77], v[76:77], 0, v[48:49]
	v_lshrrev_b32_e32 v75, 16, v75
	v_lshrrev_b32_e32 v95, 16, v79
	v_lshrrev_b32_e32 v96, 16, v78
	v_lshl_add_u64 v[78:79], v[76:77], 0, s[4:5]
	v_add_co_u32_e32 v76, vcc, s35, v76
	v_lshrrev_b32_e32 v97, 16, v83
	v_lshrrev_b32_e32 v98, 16, v82
	v_perm_b32 v83, v93, v94, s34
	v_perm_b32 v82, v92, v75, s34
	v_addc_co_u32_e32 v77, vcc, 0, v77, vcc
	v_lshrrev_b32_e32 v86, 16, v86
	v_lshrrev_b32_e32 v85, 16, v85
	v_lshrrev_b32_e32 v88, 16, v88
	v_lshrrev_b32_e32 v87, 16, v87
	global_store_dwordx2 v[76:77], v[82:83], off offset:2048
	v_perm_b32 v77, v97, v98, s34
	v_perm_b32 v76, v95, v96, s34
	v_lshrrev_b32_e32 v90, 16, v90
	v_lshrrev_b32_e32 v89, 16, v89
	v_lshrrev_b32_e32 v63, 16, v63
	v_lshrrev_b32_e32 v91, 16, v91
	global_store_dwordx2 v[78:79], v[76:77], off offset:16
	v_perm_b32 v77, v88, v87, s34
	v_perm_b32 v76, v86, v85, s34
	global_store_dwordx2 v[78:79], v[76:77], off offset:32
	v_perm_b32 v77, v63, v91, s34
	v_perm_b32 v76, v90, v89, s34
	global_store_dwordx2 v[78:79], v[76:77], off offset:48

.LBB0_1854:
	s_abs_i32 s1, s22
	s_mul_hi_u32 s4, s1, s12
	s_mul_i32 s5, s4, s11
	s_ashr_i32 s0, s22, 31
	s_sub_i32 s1, s1, s5
	s_xor_b32 s0, s0, s10
	s_add_i32 s5, s4, 1
	s_sub_i32 s23, s1, s11
	s_cmp_ge_u32 s1, s11
	s_cselect_b32 s4, s5, s4
	s_cselect_b32 s1, s23, s1
	s_add_i32 s5, s4, 1
	s_cmp_ge_u32 s1, s11
	s_cselect_b32 s1, s5, s4
	s_xor_b32 s1, s1, s0
	s_sub_i32 s0, s1, s0
	s_lshl_b32 s1, s0, 3
	s_mul_i32 s4, s13, s1
	s_add_i32 s4, s22, s4
	s_and_b32 s5, s22, 7
	s_lshr_b32 s4, s4, 3
	s_or_b32 s1, s1, s5
	v_readlane_b32 s5, v252, 40
	s_add_i32 s4, s4, s5
	v_mov_b32_e32 v84, v218
	s_lshl_b32 s4, s4, 7
	s_lshl_b32 s1, s1, 7
	v_ashrrev_i32_e32 v3, 3, v84
	v_add_u32_e32 v0, s4, v3
	v_ashrrev_i32_e32 v1, 31, v0
	v_lshlrev_b64 v[0:1], 11, v[0:1]
	s_waitcnt vmcnt(2)
	v_lshlrev_b32_e32 v4, 4, v84
	v_lshl_add_u64 v[0:1], s[6:7], 0, v[0:1]
	v_and_b32_e32 v64, 0x70, v4
	v_lshl_add_u64 v[66:67], v[0:1], 0, v[64:65]
	v_add_u32_e32 v0, s1, v3
	v_ashrrev_i32_e32 v1, 31, v0
	v_readlane_b32 s24, v250, 13
	v_lshlrev_b64 v[0:1], 11, v[0:1]
	v_readlane_b32 s25, v250, 14
	v_add_co_u32_e32 v70, vcc, s14, v66
	s_nop 0
	v_lshl_add_u64 v[0:1], s[24:25], 0, v[0:1]
	v_lshl_add_u64 v[68:69], v[0:1], 0, v[64:65]
	v_lshrrev_b32_e32 v0, 4, v84
	v_addc_co_u32_e32 v71, vcc, 0, v67, vcc
	v_xor_b32_e32 v0, v0, v84
	v_ashrrev_i32_e32 v1, 1, v84
	v_add_co_u32_e32 v72, vcc, s15, v66
	v_and_b32_e32 v85, 31, v84
	v_lshlrev_b32_e32 v0, 4, v0
	v_and_b32_e32 v64, 0xffffffc0, v1
	v_addc_co_u32_e32 v73, vcc, 0, v67, vcc
	v_and_b32_e32 v0, 0x70, v0
	v_or_b32_e32 v1, v64, v85
	v_add_co_u32_e32 v74, vcc, s16, v66
	v_lshrrev_b32_e32 v2, 5, v84
	v_bfe_u32 v86, v84, 5, 1
	v_lshl_or_b32 v87, v3, 7, v0
	v_bfe_u32 v0, v84, 1, 3
	s_waitcnt vmcnt(0)
	v_lshlrev_b32_e32 v32, 7, v1
	v_lshlrev_b32_e32 v1, 7, v84
	v_addc_co_u32_e32 v75, vcc, 0, v67, vcc
	v_and_b32_e32 v33, 0x2f80, v1
	v_bitop3_b32 v34, v2, v0, 1 bitop3:0x6c
	v_bitop3_b32 v35, v86, v0, 2 bitop3:0x36
	v_bitop3_b32 v36, v86, v0, 4 bitop3:0x36
	v_bitop3_b32 v37, v86, v0, 6 bitop3:0x36
	global_load_dwordx4 v[0:3], v[66:67], off
	global_load_dwordx4 v[4:7], v[70:71], off
	global_load_dwordx4 v[8:11], v[72:73], off
	global_load_dwordx4 v[12:15], v[74:75], off
	global_load_dwordx4 v[16:19], v[68:69], off
	v_add_co_u32_e32 v76, vcc, s14, v68
	s_nop 1
	v_addc_co_u32_e32 v77, vcc, 0, v69, vcc
	v_add_co_u32_e32 v78, vcc, s15, v68
	global_load_dwordx4 v[20:23], v[76:77], off
	s_nop 0
	v_addc_co_u32_e32 v79, vcc, 0, v69, vcc
	global_load_dwordx4 v[24:27], v[78:79], off
	v_add_co_u32_e32 v82, vcc, s16, v68
	s_nop 1
	v_addc_co_u32_e32 v83, vcc, 0, v69, vcc
	global_load_dwordx4 v[28:31], v[82:83], off
	global_load_dwordx4 v[96:99], v[66:67], off offset:128
	global_load_dwordx4 v[100:103], v[70:71], off offset:128
	global_load_dwordx4 v[104:107], v[72:73], off offset:128
	global_load_dwordx4 v[108:111], v[74:75], off offset:128
	global_load_dwordx4 v[112:115], v[68:69], off offset:128
	global_load_dwordx4 v[116:119], v[76:77], off offset:128
	global_load_dwordx4 v[120:123], v[78:79], off offset:128
	global_load_dwordx4 v[124:127], v[82:83], off offset:128
	s_waitcnt vmcnt(15)
	ds_write_b128 v87, v[0:3]
	s_waitcnt vmcnt(14)
	ds_write_b128 v87, v[4:7] offset:4096
	s_waitcnt vmcnt(13)
	ds_write_b128 v87, v[8:11] offset:8192
	s_waitcnt vmcnt(12)
	ds_write_b128 v87, v[12:15] offset:12288
	s_waitcnt vmcnt(11)
	ds_write_b128 v87, v[16:19] offset:32768
	s_waitcnt vmcnt(10)
	ds_write_b128 v87, v[20:23] offset:36864
	s_waitcnt vmcnt(9)
	ds_write_b128 v87, v[24:27] offset:40960
	s_waitcnt vmcnt(8)
	ds_write_b128 v87, v[28:31] offset:45056
	s_waitcnt lgkmcnt(0)
	s_barrier
	global_load_dwordx4 v[128:131], v[66:67], off offset:256
	global_load_dwordx4 v[132:135], v[70:71], off offset:256
	global_load_dwordx4 v[136:139], v[72:73], off offset:256
	global_load_dwordx4 v[140:143], v[74:75], off offset:256
	global_load_dwordx4 v[144:147], v[68:69], off offset:256
	global_load_dwordx4 v[148:151], v[76:77], off offset:256
	global_load_dwordx4 v[152:155], v[78:79], off offset:256
	global_load_dwordx4 v[156:159], v[82:83], off offset:256
	v_lshlrev_b32_e32 v0, 4, v34
	v_or_b32_e32 v95, v32, v0
	v_or_b32_e32 v94, v33, v0
	v_lshlrev_b32_e32 v0, 4, v35
	v_or_b32_e32 v93, v32, v0
	v_or_b32_e32 v92, v33, v0
	v_lshlrev_b32_e32 v0, 4, v36
	v_or_b32_e32 v91, v32, v0
	v_or_b32_e32 v90, v33, v0
	v_lshlrev_b32_e32 v0, 4, v37
	v_or_b32_e32 v89, v32, v0
	v_or_b32_e32 v88, v33, v0
	ds_read_b128 v[160:163], v95
	ds_read_b128 v[164:167], v94 offset:32768
	ds_read_b128 v[168:171], v95 offset:4096
	ds_read_b128 v[172:175], v94 offset:36864
	ds_read_b128 v[188:191], v93
	ds_read_b128 v[192:195], v92 offset:32768
	ds_read_b128 v[196:199], v93 offset:4096
	ds_read_b128 v[200:203], v92 offset:36864
	s_waitcnt lgkmcnt(4)
	v_mfma_f32_32x32x16_bf16 v[48:63], v[160:163], v[164:167], 0
	v_mfma_f32_32x32x16_bf16 v[32:47], v[160:163], v[172:175], 0
	v_mfma_f32_32x32x16_bf16 v[16:31], v[168:171], v[164:167], 0
	v_mfma_f32_32x32x16_bf16 v[0:15], v[168:171], v[172:175], 0
	ds_read_b128 v[160:163], v91
	ds_read_b128 v[164:167], v90 offset:32768
	ds_read_b128 v[168:171], v91 offset:4096
	ds_read_b128 v[172:175], v90 offset:36864
	s_waitcnt lgkmcnt(4)
	s_waitcnt vmcnt(8)
	v_mfma_f32_32x32x16_bf16 v[48:63], v[188:191], v[192:195], v[48:63]
	ds_write_b128 v87, v[96:99] offset:16384
	v_mfma_f32_32x32x16_bf16 v[32:47], v[188:191], v[200:203], v[32:47]
	ds_write_b128 v87, v[100:103] offset:20480
	v_mfma_f32_32x32x16_bf16 v[16:31], v[196:199], v[192:195], v[16:31]
	ds_write_b128 v87, v[104:107] offset:24576
	v_mfma_f32_32x32x16_bf16 v[0:15], v[196:199], v[200:203], v[0:15]
	ds_write_b128 v87, v[108:111] offset:28672
	ds_read_b128 v[188:191], v89
	ds_read_b128 v[192:195], v88 offset:32768
	ds_read_b128 v[196:199], v89 offset:4096
	ds_read_b128 v[200:203], v88 offset:36864
	s_waitcnt lgkmcnt(8)
	v_mfma_f32_32x32x16_bf16 v[48:63], v[160:163], v[164:167], v[48:63]
	ds_write_b128 v87, v[112:115] offset:49152
	v_mfma_f32_32x32x16_bf16 v[32:47], v[160:163], v[172:175], v[32:47]
	ds_write_b128 v87, v[116:119] offset:53248
	v_mfma_f32_32x32x16_bf16 v[16:31], v[168:171], v[164:167], v[16:31]
	ds_write_b128 v87, v[120:123] offset:57344
	v_mfma_f32_32x32x16_bf16 v[0:15], v[168:171], v[172:175], v[0:15]
	ds_write_b128 v87, v[124:127] offset:61440
	s_waitcnt lgkmcnt(0)
	s_barrier
	ds_read_b128 v[160:163], v95 offset:16384
	ds_read_b128 v[164:167], v94 offset:49152
	ds_read_b128 v[168:171], v95 offset:20480
	ds_read_b128 v[172:175], v94 offset:53248
	v_mfma_f32_32x32x16_bf16 v[48:63], v[188:191], v[192:195], v[48:63]
	global_load_dwordx4 v[96:99], v[66:67], off offset:384
	v_mfma_f32_32x32x16_bf16 v[32:47], v[188:191], v[200:203], v[32:47]
	global_load_dwordx4 v[100:103], v[70:71], off offset:384
	v_mfma_f32_32x32x16_bf16 v[16:31], v[196:199], v[192:195], v[16:31]
	global_load_dwordx4 v[104:107], v[72:73], off offset:384
	v_mfma_f32_32x32x16_bf16 v[0:15], v[196:199], v[200:203], v[0:15]
	global_load_dwordx4 v[108:111], v[74:75], off offset:384
	ds_read_b128 v[188:191], v93 offset:16384
	ds_read_b128 v[192:195], v92 offset:49152
	ds_read_b128 v[196:199], v93 offset:20480
	ds_read_b128 v[200:203], v92 offset:53248
	s_waitcnt lgkmcnt(4)
	v_mfma_f32_32x32x16_bf16 v[48:63], v[160:163], v[164:167], v[48:63]
	global_load_dwordx4 v[112:115], v[68:69], off offset:384
	v_mfma_f32_32x32x16_bf16 v[32:47], v[160:163], v[172:175], v[32:47]
	global_load_dwordx4 v[116:119], v[76:77], off offset:384
	v_mfma_f32_32x32x16_bf16 v[16:31], v[168:171], v[164:167], v[16:31]
	global_load_dwordx4 v[120:123], v[78:79], off offset:384
	v_mfma_f32_32x32x16_bf16 v[0:15], v[168:171], v[172:175], v[0:15]
	global_load_dwordx4 v[124:127], v[82:83], off offset:384
	ds_read_b128 v[160:163], v91 offset:16384
	ds_read_b128 v[164:167], v90 offset:49152
	ds_read_b128 v[168:171], v91 offset:20480
	ds_read_b128 v[172:175], v90 offset:53248
	s_waitcnt lgkmcnt(4)
	s_waitcnt vmcnt(8)
	v_mfma_f32_32x32x16_bf16 v[48:63], v[188:191], v[192:195], v[48:63]
	ds_write_b128 v87, v[128:131]
	v_mfma_f32_32x32x16_bf16 v[32:47], v[188:191], v[200:203], v[32:47]
	ds_write_b128 v87, v[132:135] offset:4096
	v_mfma_f32_32x32x16_bf16 v[16:31], v[196:199], v[192:195], v[16:31]
	ds_write_b128 v87, v[136:139] offset:8192
	v_mfma_f32_32x32x16_bf16 v[0:15], v[196:199], v[200:203], v[0:15]
	ds_write_b128 v87, v[140:143] offset:12288
	ds_read_b128 v[188:191], v89 offset:16384
	ds_read_b128 v[192:195], v88 offset:49152
	ds_read_b128 v[196:199], v89 offset:20480
	ds_read_b128 v[200:203], v88 offset:53248
	s_waitcnt lgkmcnt(8)
	v_mfma_f32_32x32x16_bf16 v[48:63], v[160:163], v[164:167], v[48:63]
	ds_write_b128 v87, v[144:147] offset:32768
	v_mfma_f32_32x32x16_bf16 v[32:47], v[160:163], v[172:175], v[32:47]
	ds_write_b128 v87, v[148:151] offset:36864
	v_mfma_f32_32x32x16_bf16 v[16:31], v[168:171], v[164:167], v[16:31]
	ds_write_b128 v87, v[152:155] offset:40960
	v_mfma_f32_32x32x16_bf16 v[0:15], v[168:171], v[172:175], v[0:15]
	ds_write_b128 v87, v[156:159] offset:45056
	s_waitcnt lgkmcnt(0)
	s_barrier
	ds_read_b128 v[160:163], v95
	ds_read_b128 v[164:167], v94 offset:32768
	ds_read_b128 v[168:171], v95 offset:4096
	ds_read_b128 v[172:175], v94 offset:36864
	v_mfma_f32_32x32x16_bf16 v[48:63], v[188:191], v[192:195], v[48:63]
	global_load_dwordx4 v[128:131], v[66:67], off offset:512
	v_mfma_f32_32x32x16_bf16 v[32:47], v[188:191], v[200:203], v[32:47]
	global_load_dwordx4 v[132:135], v[70:71], off offset:512
	v_mfma_f32_32x32x16_bf16 v[16:31], v[196:199], v[192:195], v[16:31]
	global_load_dwordx4 v[136:139], v[72:73], off offset:512
	v_mfma_f32_32x32x16_bf16 v[0:15], v[196:199], v[200:203], v[0:15]
	global_load_dwordx4 v[140:143], v[74:75], off offset:512
	ds_read_b128 v[188:191], v93
	ds_read_b128 v[192:195], v92 offset:32768
	ds_read_b128 v[196:199], v93 offset:4096
	ds_read_b128 v[200:203], v92 offset:36864
	s_waitcnt lgkmcnt(4)
	v_mfma_f32_32x32x16_bf16 v[48:63], v[160:163], v[164:167], v[48:63]
	global_load_dwordx4 v[144:147], v[68:69], off offset:512
	v_mfma_f32_32x32x16_bf16 v[32:47], v[160:163], v[172:175], v[32:47]
	global_load_dwordx4 v[148:151], v[76:77], off offset:512
	v_mfma_f32_32x32x16_bf16 v[16:31], v[168:171], v[164:167], v[16:31]
	global_load_dwordx4 v[152:155], v[78:79], off offset:512
	v_mfma_f32_32x32x16_bf16 v[0:15], v[168:171], v[172:175], v[0:15]
	global_load_dwordx4 v[156:159], v[82:83], off offset:512
	ds_read_b128 v[160:163], v91
	ds_read_b128 v[164:167], v90 offset:32768
	ds_read_b128 v[168:171], v91 offset:4096
	ds_read_b128 v[172:175], v90 offset:36864
	s_waitcnt lgkmcnt(4)
	s_waitcnt vmcnt(8)
	v_mfma_f32_32x32x16_bf16 v[48:63], v[188:191], v[192:195], v[48:63]
	ds_write_b128 v87, v[96:99] offset:16384
	v_mfma_f32_32x32x16_bf16 v[32:47], v[188:191], v[200:203], v[32:47]
	ds_write_b128 v87, v[100:103] offset:20480
	v_mfma_f32_32x32x16_bf16 v[16:31], v[196:199], v[192:195], v[16:31]
	ds_write_b128 v87, v[104:107] offset:24576
	v_mfma_f32_32x32x16_bf16 v[0:15], v[196:199], v[200:203], v[0:15]
	ds_write_b128 v87, v[108:111] offset:28672
	ds_read_b128 v[188:191], v89
	ds_read_b128 v[192:195], v88 offset:32768
	ds_read_b128 v[196:199], v89 offset:4096
	ds_read_b128 v[200:203], v88 offset:36864
	s_waitcnt lgkmcnt(8)
	v_mfma_f32_32x32x16_bf16 v[48:63], v[160:163], v[164:167], v[48:63]
	ds_write_b128 v87, v[112:115] offset:49152
	v_mfma_f32_32x32x16_bf16 v[32:47], v[160:163], v[172:175], v[32:47]
	ds_write_b128 v87, v[116:119] offset:53248
	v_mfma_f32_32x32x16_bf16 v[16:31], v[168:171], v[164:167], v[16:31]
	ds_write_b128 v87, v[120:123] offset:57344
	v_mfma_f32_32x32x16_bf16 v[0:15], v[168:171], v[172:175], v[0:15]
	ds_write_b128 v87, v[124:127] offset:61440
	s_waitcnt lgkmcnt(0)
	s_barrier
	ds_read_b128 v[160:163], v95 offset:16384
	ds_read_b128 v[164:167], v94 offset:49152
	ds_read_b128 v[168:171], v95 offset:20480
	ds_read_b128 v[172:175], v94 offset:53248
	v_mfma_f32_32x32x16_bf16 v[48:63], v[188:191], v[192:195], v[48:63]
	global_load_dwordx4 v[96:99], v[66:67], off offset:640
	v_mfma_f32_32x32x16_bf16 v[32:47], v[188:191], v[200:203], v[32:47]
	global_load_dwordx4 v[100:103], v[70:71], off offset:640
	v_mfma_f32_32x32x16_bf16 v[16:31], v[196:199], v[192:195], v[16:31]
	global_load_dwordx4 v[104:107], v[72:73], off offset:640
	v_mfma_f32_32x32x16_bf16 v[0:15], v[196:199], v[200:203], v[0:15]
	global_load_dwordx4 v[108:111], v[74:75], off offset:640
	ds_read_b128 v[188:191], v93 offset:16384
	ds_read_b128 v[192:195], v92 offset:49152
	ds_read_b128 v[196:199], v93 offset:20480
	ds_read_b128 v[200:203], v92 offset:53248
	s_waitcnt lgkmcnt(4)
	v_mfma_f32_32x32x16_bf16 v[48:63], v[160:163], v[164:167], v[48:63]
	global_load_dwordx4 v[112:115], v[68:69], off offset:640
	v_mfma_f32_32x32x16_bf16 v[32:47], v[160:163], v[172:175], v[32:47]
	global_load_dwordx4 v[116:119], v[76:77], off offset:640
	v_mfma_f32_32x32x16_bf16 v[16:31], v[168:171], v[164:167], v[16:31]
	global_load_dwordx4 v[120:123], v[78:79], off offset:640
	v_mfma_f32_32x32x16_bf16 v[0:15], v[168:171], v[172:175], v[0:15]
	global_load_dwordx4 v[124:127], v[82:83], off offset:640
	ds_read_b128 v[160:163], v91 offset:16384
	ds_read_b128 v[164:167], v90 offset:49152
	ds_read_b128 v[168:171], v91 offset:20480
	ds_read_b128 v[172:175], v90 offset:53248
	s_waitcnt lgkmcnt(4)
	s_waitcnt vmcnt(8)
	v_mfma_f32_32x32x16_bf16 v[48:63], v[188:191], v[192:195], v[48:63]
	ds_write_b128 v87, v[128:131]
	v_mfma_f32_32x32x16_bf16 v[32:47], v[188:191], v[200:203], v[32:47]
	ds_write_b128 v87, v[132:135] offset:4096
	v_mfma_f32_32x32x16_bf16 v[16:31], v[196:199], v[192:195], v[16:31]
	ds_write_b128 v87, v[136:139] offset:8192
	v_mfma_f32_32x32x16_bf16 v[0:15], v[196:199], v[200:203], v[0:15]
	ds_write_b128 v87, v[140:143] offset:12288
	ds_read_b128 v[188:191], v89 offset:16384
	ds_read_b128 v[192:195], v88 offset:49152
	ds_read_b128 v[196:199], v89 offset:20480
	ds_read_b128 v[200:203], v88 offset:53248
	s_waitcnt lgkmcnt(8)
	v_mfma_f32_32x32x16_bf16 v[48:63], v[160:163], v[164:167], v[48:63]
	ds_write_b128 v87, v[144:147] offset:32768
	v_mfma_f32_32x32x16_bf16 v[32:47], v[160:163], v[172:175], v[32:47]
	ds_write_b128 v87, v[148:151] offset:36864
	v_mfma_f32_32x32x16_bf16 v[16:31], v[168:171], v[164:167], v[16:31]
	ds_write_b128 v87, v[152:155] offset:40960
	v_mfma_f32_32x32x16_bf16 v[0:15], v[168:171], v[172:175], v[0:15]
	ds_write_b128 v87, v[156:159] offset:45056
	s_waitcnt lgkmcnt(0)
	s_barrier
	ds_read_b128 v[160:163], v95
	ds_read_b128 v[164:167], v94 offset:32768
	ds_read_b128 v[168:171], v95 offset:4096
	ds_read_b128 v[172:175], v94 offset:36864
	v_mfma_f32_32x32x16_bf16 v[48:63], v[188:191], v[192:195], v[48:63]
	global_load_dwordx4 v[128:131], v[66:67], off offset:768
	v_mfma_f32_32x32x16_bf16 v[32:47], v[188:191], v[200:203], v[32:47]
	global_load_dwordx4 v[132:135], v[70:71], off offset:768
	v_mfma_f32_32x32x16_bf16 v[16:31], v[196:199], v[192:195], v[16:31]
	global_load_dwordx4 v[136:139], v[72:73], off offset:768
	v_mfma_f32_32x32x16_bf16 v[0:15], v[196:199], v[200:203], v[0:15]
	global_load_dwordx4 v[140:143], v[74:75], off offset:768
	ds_read_b128 v[188:191], v93
	ds_read_b128 v[192:195], v92 offset:32768
	ds_read_b128 v[196:199], v93 offset:4096
	ds_read_b128 v[200:203], v92 offset:36864
	s_waitcnt lgkmcnt(4)
	v_mfma_f32_32x32x16_bf16 v[48:63], v[160:163], v[164:167], v[48:63]
	global_load_dwordx4 v[144:147], v[68:69], off offset:768
	v_mfma_f32_32x32x16_bf16 v[32:47], v[160:163], v[172:175], v[32:47]
	global_load_dwordx4 v[148:151], v[76:77], off offset:768
	v_mfma_f32_32x32x16_bf16 v[16:31], v[168:171], v[164:167], v[16:31]
	global_load_dwordx4 v[152:155], v[78:79], off offset:768
	v_mfma_f32_32x32x16_bf16 v[0:15], v[168:171], v[172:175], v[0:15]
	global_load_dwordx4 v[156:159], v[82:83], off offset:768
	ds_read_b128 v[160:163], v91
	ds_read_b128 v[164:167], v90 offset:32768
	ds_read_b128 v[168:171], v91 offset:4096
	ds_read_b128 v[172:175], v90 offset:36864
	s_waitcnt lgkmcnt(4)
	s_waitcnt vmcnt(8)
	v_mfma_f32_32x32x16_bf16 v[48:63], v[188:191], v[192:195], v[48:63]
	ds_write_b128 v87, v[96:99] offset:16384
	v_mfma_f32_32x32x16_bf16 v[32:47], v[188:191], v[200:203], v[32:47]
	ds_write_b128 v87, v[100:103] offset:20480
	v_mfma_f32_32x32x16_bf16 v[16:31], v[196:199], v[192:195], v[16:31]
	ds_write_b128 v87, v[104:107] offset:24576
	v_mfma_f32_32x32x16_bf16 v[0:15], v[196:199], v[200:203], v[0:15]
	ds_write_b128 v87, v[108:111] offset:28672
	ds_read_b128 v[188:191], v89
	ds_read_b128 v[192:195], v88 offset:32768
	ds_read_b128 v[196:199], v89 offset:4096
	ds_read_b128 v[200:203], v88 offset:36864
	s_waitcnt lgkmcnt(8)
	v_mfma_f32_32x32x16_bf16 v[48:63], v[160:163], v[164:167], v[48:63]
	ds_write_b128 v87, v[112:115] offset:49152
	v_mfma_f32_32x32x16_bf16 v[32:47], v[160:163], v[172:175], v[32:47]
	ds_write_b128 v87, v[116:119] offset:53248
	v_mfma_f32_32x32x16_bf16 v[16:31], v[168:171], v[164:167], v[16:31]
	ds_write_b128 v87, v[120:123] offset:57344
	v_mfma_f32_32x32x16_bf16 v[0:15], v[168:171], v[172:175], v[0:15]
	ds_write_b128 v87, v[124:127] offset:61440
	s_waitcnt lgkmcnt(0)
	s_barrier
	ds_read_b128 v[160:163], v95 offset:16384
	ds_read_b128 v[164:167], v94 offset:49152
	ds_read_b128 v[168:171], v95 offset:20480
	ds_read_b128 v[172:175], v94 offset:53248
	v_mfma_f32_32x32x16_bf16 v[48:63], v[188:191], v[192:195], v[48:63]
	global_load_dwordx4 v[96:99], v[66:67], off offset:896
	v_mfma_f32_32x32x16_bf16 v[32:47], v[188:191], v[200:203], v[32:47]
	global_load_dwordx4 v[100:103], v[70:71], off offset:896
	v_mfma_f32_32x32x16_bf16 v[16:31], v[196:199], v[192:195], v[16:31]
	global_load_dwordx4 v[104:107], v[72:73], off offset:896
	v_mfma_f32_32x32x16_bf16 v[0:15], v[196:199], v[200:203], v[0:15]
	global_load_dwordx4 v[108:111], v[74:75], off offset:896
	ds_read_b128 v[188:191], v93 offset:16384
	ds_read_b128 v[192:195], v92 offset:49152
	ds_read_b128 v[196:199], v93 offset:20480
	ds_read_b128 v[200:203], v92 offset:53248
	s_waitcnt lgkmcnt(4)
	v_mfma_f32_32x32x16_bf16 v[48:63], v[160:163], v[164:167], v[48:63]
	global_load_dwordx4 v[112:115], v[68:69], off offset:896
	v_mfma_f32_32x32x16_bf16 v[32:47], v[160:163], v[172:175], v[32:47]
	global_load_dwordx4 v[116:119], v[76:77], off offset:896
	v_mfma_f32_32x32x16_bf16 v[16:31], v[168:171], v[164:167], v[16:31]
	global_load_dwordx4 v[120:123], v[78:79], off offset:896
	v_mfma_f32_32x32x16_bf16 v[0:15], v[168:171], v[172:175], v[0:15]
	global_load_dwordx4 v[124:127], v[82:83], off offset:896
	ds_read_b128 v[160:163], v91 offset:16384
	ds_read_b128 v[164:167], v90 offset:49152
	ds_read_b128 v[168:171], v91 offset:20480
	ds_read_b128 v[172:175], v90 offset:53248
	s_waitcnt lgkmcnt(4)
	s_waitcnt vmcnt(8)
	v_mfma_f32_32x32x16_bf16 v[48:63], v[188:191], v[192:195], v[48:63]
	ds_write_b128 v87, v[128:131]
	v_mfma_f32_32x32x16_bf16 v[32:47], v[188:191], v[200:203], v[32:47]
	ds_write_b128 v87, v[132:135] offset:4096
	v_mfma_f32_32x32x16_bf16 v[16:31], v[196:199], v[192:195], v[16:31]
	ds_write_b128 v87, v[136:139] offset:8192
	v_mfma_f32_32x32x16_bf16 v[0:15], v[196:199], v[200:203], v[0:15]
	ds_write_b128 v87, v[140:143] offset:12288
	ds_read_b128 v[188:191], v89 offset:16384
	ds_read_b128 v[192:195], v88 offset:49152
	ds_read_b128 v[196:199], v89 offset:20480
	ds_read_b128 v[200:203], v88 offset:53248
	s_waitcnt lgkmcnt(8)
	v_mfma_f32_32x32x16_bf16 v[48:63], v[160:163], v[164:167], v[48:63]
	ds_write_b128 v87, v[144:147] offset:32768
	v_mfma_f32_32x32x16_bf16 v[32:47], v[160:163], v[172:175], v[32:47]
	ds_write_b128 v87, v[148:151] offset:36864
	v_mfma_f32_32x32x16_bf16 v[16:31], v[168:171], v[164:167], v[16:31]
	ds_write_b128 v87, v[152:155] offset:40960
	v_mfma_f32_32x32x16_bf16 v[0:15], v[168:171], v[172:175], v[0:15]
	ds_write_b128 v87, v[156:159] offset:45056
	s_waitcnt lgkmcnt(0)
	s_barrier
	ds_read_b128 v[160:163], v95
	ds_read_b128 v[164:167], v94 offset:32768
	ds_read_b128 v[168:171], v95 offset:4096
	ds_read_b128 v[172:175], v94 offset:36864
	v_mfma_f32_32x32x16_bf16 v[48:63], v[188:191], v[192:195], v[48:63]
	global_load_dwordx4 v[128:131], v[66:67], off offset:1024
	v_mfma_f32_32x32x16_bf16 v[32:47], v[188:191], v[200:203], v[32:47]
	global_load_dwordx4 v[132:135], v[70:71], off offset:1024
	v_mfma_f32_32x32x16_bf16 v[16:31], v[196:199], v[192:195], v[16:31]
	global_load_dwordx4 v[136:139], v[72:73], off offset:1024
	v_mfma_f32_32x32x16_bf16 v[0:15], v[196:199], v[200:203], v[0:15]
	global_load_dwordx4 v[140:143], v[74:75], off offset:1024
	ds_read_b128 v[188:191], v93
	ds_read_b128 v[192:195], v92 offset:32768
	ds_read_b128 v[196:199], v93 offset:4096
	ds_read_b128 v[200:203], v92 offset:36864
	s_waitcnt lgkmcnt(4)
	v_mfma_f32_32x32x16_bf16 v[48:63], v[160:163], v[164:167], v[48:63]
	global_load_dwordx4 v[144:147], v[68:69], off offset:1024
	v_mfma_f32_32x32x16_bf16 v[32:47], v[160:163], v[172:175], v[32:47]
	global_load_dwordx4 v[148:151], v[76:77], off offset:1024
	v_mfma_f32_32x32x16_bf16 v[16:31], v[168:171], v[164:167], v[16:31]
	global_load_dwordx4 v[152:155], v[78:79], off offset:1024
	v_mfma_f32_32x32x16_bf16 v[0:15], v[168:171], v[172:175], v[0:15]
	global_load_dwordx4 v[156:159], v[82:83], off offset:1024
	ds_read_b128 v[160:163], v91
	ds_read_b128 v[164:167], v90 offset:32768
	ds_read_b128 v[168:171], v91 offset:4096
	ds_read_b128 v[172:175], v90 offset:36864
	s_waitcnt lgkmcnt(4)
	s_waitcnt vmcnt(8)
	v_mfma_f32_32x32x16_bf16 v[48:63], v[188:191], v[192:195], v[48:63]
	ds_write_b128 v87, v[96:99] offset:16384
	v_mfma_f32_32x32x16_bf16 v[32:47], v[188:191], v[200:203], v[32:47]
	ds_write_b128 v87, v[100:103] offset:20480
	v_mfma_f32_32x32x16_bf16 v[16:31], v[196:199], v[192:195], v[16:31]
	ds_write_b128 v87, v[104:107] offset:24576
	v_mfma_f32_32x32x16_bf16 v[0:15], v[196:199], v[200:203], v[0:15]
	ds_write_b128 v87, v[108:111] offset:28672
	ds_read_b128 v[188:191], v89
	ds_read_b128 v[192:195], v88 offset:32768
	ds_read_b128 v[196:199], v89 offset:4096
	ds_read_b128 v[200:203], v88 offset:36864
	s_waitcnt lgkmcnt(8)
	v_mfma_f32_32x32x16_bf16 v[48:63], v[160:163], v[164:167], v[48:63]
	ds_write_b128 v87, v[112:115] offset:49152
	v_mfma_f32_32x32x16_bf16 v[32:47], v[160:163], v[172:175], v[32:47]
	ds_write_b128 v87, v[116:119] offset:53248
	v_mfma_f32_32x32x16_bf16 v[16:31], v[168:171], v[164:167], v[16:31]
	ds_write_b128 v87, v[120:123] offset:57344
	v_mfma_f32_32x32x16_bf16 v[0:15], v[168:171], v[172:175], v[0:15]
	ds_write_b128 v87, v[124:127] offset:61440
	s_waitcnt lgkmcnt(0)
	s_barrier
	ds_read_b128 v[160:163], v95 offset:16384
	ds_read_b128 v[164:167], v94 offset:49152
	ds_read_b128 v[168:171], v95 offset:20480
	ds_read_b128 v[172:175], v94 offset:53248
	v_mfma_f32_32x32x16_bf16 v[48:63], v[188:191], v[192:195], v[48:63]
	global_load_dwordx4 v[96:99], v[66:67], off offset:1152
	v_mfma_f32_32x32x16_bf16 v[32:47], v[188:191], v[200:203], v[32:47]
	global_load_dwordx4 v[100:103], v[70:71], off offset:1152
	v_mfma_f32_32x32x16_bf16 v[16:31], v[196:199], v[192:195], v[16:31]
	global_load_dwordx4 v[104:107], v[72:73], off offset:1152
	v_mfma_f32_32x32x16_bf16 v[0:15], v[196:199], v[200:203], v[0:15]
	global_load_dwordx4 v[108:111], v[74:75], off offset:1152
	ds_read_b128 v[188:191], v93 offset:16384
	ds_read_b128 v[192:195], v92 offset:49152
	ds_read_b128 v[196:199], v93 offset:20480
	ds_read_b128 v[200:203], v92 offset:53248
	s_waitcnt lgkmcnt(4)
	v_mfma_f32_32x32x16_bf16 v[48:63], v[160:163], v[164:167], v[48:63]
	global_load_dwordx4 v[112:115], v[68:69], off offset:1152
	v_mfma_f32_32x32x16_bf16 v[32:47], v[160:163], v[172:175], v[32:47]
	global_load_dwordx4 v[116:119], v[76:77], off offset:1152
	v_mfma_f32_32x32x16_bf16 v[16:31], v[168:171], v[164:167], v[16:31]
	global_load_dwordx4 v[120:123], v[78:79], off offset:1152
	v_mfma_f32_32x32x16_bf16 v[0:15], v[168:171], v[172:175], v[0:15]
	global_load_dwordx4 v[124:127], v[82:83], off offset:1152
	ds_read_b128 v[160:163], v91 offset:16384
	ds_read_b128 v[164:167], v90 offset:49152
	ds_read_b128 v[168:171], v91 offset:20480
	ds_read_b128 v[172:175], v90 offset:53248
	s_waitcnt lgkmcnt(4)
	s_waitcnt vmcnt(8)
	v_mfma_f32_32x32x16_bf16 v[48:63], v[188:191], v[192:195], v[48:63]
	ds_write_b128 v87, v[128:131]
	v_mfma_f32_32x32x16_bf16 v[32:47], v[188:191], v[200:203], v[32:47]
	ds_write_b128 v87, v[132:135] offset:4096
	v_mfma_f32_32x32x16_bf16 v[16:31], v[196:199], v[192:195], v[16:31]
	ds_write_b128 v87, v[136:139] offset:8192
	v_mfma_f32_32x32x16_bf16 v[0:15], v[196:199], v[200:203], v[0:15]
	ds_write_b128 v87, v[140:143] offset:12288
	ds_read_b128 v[188:191], v89 offset:16384
	ds_read_b128 v[192:195], v88 offset:49152
	ds_read_b128 v[196:199], v89 offset:20480
	ds_read_b128 v[200:203], v88 offset:53248
	s_waitcnt lgkmcnt(8)
	v_mfma_f32_32x32x16_bf16 v[48:63], v[160:163], v[164:167], v[48:63]
	ds_write_b128 v87, v[144:147] offset:32768
	v_mfma_f32_32x32x16_bf16 v[32:47], v[160:163], v[172:175], v[32:47]
	ds_write_b128 v87, v[148:151] offset:36864
	v_mfma_f32_32x32x16_bf16 v[16:31], v[168:171], v[164:167], v[16:31]
	ds_write_b128 v87, v[152:155] offset:40960
	v_mfma_f32_32x32x16_bf16 v[0:15], v[168:171], v[172:175], v[0:15]
	ds_write_b128 v87, v[156:159] offset:45056
	s_waitcnt lgkmcnt(0)
	s_barrier
	ds_read_b128 v[160:163], v95
	ds_read_b128 v[164:167], v94 offset:32768
	ds_read_b128 v[168:171], v95 offset:4096
	ds_read_b128 v[172:175], v94 offset:36864
	v_mfma_f32_32x32x16_bf16 v[48:63], v[188:191], v[192:195], v[48:63]
	global_load_dwordx4 v[128:131], v[66:67], off offset:1280
	v_mfma_f32_32x32x16_bf16 v[32:47], v[188:191], v[200:203], v[32:47]
	global_load_dwordx4 v[132:135], v[70:71], off offset:1280
	v_mfma_f32_32x32x16_bf16 v[16:31], v[196:199], v[192:195], v[16:31]
	global_load_dwordx4 v[136:139], v[72:73], off offset:1280
	v_mfma_f32_32x32x16_bf16 v[0:15], v[196:199], v[200:203], v[0:15]
	global_load_dwordx4 v[140:143], v[74:75], off offset:1280
	ds_read_b128 v[188:191], v93
	ds_read_b128 v[192:195], v92 offset:32768
	ds_read_b128 v[196:199], v93 offset:4096
	ds_read_b128 v[200:203], v92 offset:36864
	s_waitcnt lgkmcnt(4)
	v_mfma_f32_32x32x16_bf16 v[48:63], v[160:163], v[164:167], v[48:63]
	global_load_dwordx4 v[144:147], v[68:69], off offset:1280
	v_mfma_f32_32x32x16_bf16 v[32:47], v[160:163], v[172:175], v[32:47]
	global_load_dwordx4 v[148:151], v[76:77], off offset:1280
	v_mfma_f32_32x32x16_bf16 v[16:31], v[168:171], v[164:167], v[16:31]
	global_load_dwordx4 v[152:155], v[78:79], off offset:1280
	v_mfma_f32_32x32x16_bf16 v[0:15], v[168:171], v[172:175], v[0:15]
	global_load_dwordx4 v[156:159], v[82:83], off offset:1280
	ds_read_b128 v[160:163], v91
	ds_read_b128 v[164:167], v90 offset:32768
	ds_read_b128 v[168:171], v91 offset:4096
	ds_read_b128 v[172:175], v90 offset:36864
	s_waitcnt lgkmcnt(4)
	s_waitcnt vmcnt(8)
	v_mfma_f32_32x32x16_bf16 v[48:63], v[188:191], v[192:195], v[48:63]
	ds_write_b128 v87, v[96:99] offset:16384
	v_mfma_f32_32x32x16_bf16 v[32:47], v[188:191], v[200:203], v[32:47]
	ds_write_b128 v87, v[100:103] offset:20480
	v_mfma_f32_32x32x16_bf16 v[16:31], v[196:199], v[192:195], v[16:31]
	ds_write_b128 v87, v[104:107] offset:24576
	v_mfma_f32_32x32x16_bf16 v[0:15], v[196:199], v[200:203], v[0:15]
	ds_write_b128 v87, v[108:111] offset:28672
	ds_read_b128 v[188:191], v89
	ds_read_b128 v[192:195], v88 offset:32768
	ds_read_b128 v[196:199], v89 offset:4096
	ds_read_b128 v[200:203], v88 offset:36864
	s_waitcnt lgkmcnt(8)
	v_mfma_f32_32x32x16_bf16 v[48:63], v[160:163], v[164:167], v[48:63]
	ds_write_b128 v87, v[112:115] offset:49152
	v_mfma_f32_32x32x16_bf16 v[32:47], v[160:163], v[172:175], v[32:47]
	ds_write_b128 v87, v[116:119] offset:53248
	v_mfma_f32_32x32x16_bf16 v[16:31], v[168:171], v[164:167], v[16:31]
	ds_write_b128 v87, v[120:123] offset:57344
	v_mfma_f32_32x32x16_bf16 v[0:15], v[168:171], v[172:175], v[0:15]
	ds_write_b128 v87, v[124:127] offset:61440
	s_waitcnt lgkmcnt(0)
	s_barrier
	ds_read_b128 v[160:163], v95 offset:16384
	ds_read_b128 v[164:167], v94 offset:49152
	ds_read_b128 v[168:171], v95 offset:20480
	ds_read_b128 v[172:175], v94 offset:53248
	v_mfma_f32_32x32x16_bf16 v[48:63], v[188:191], v[192:195], v[48:63]
	global_load_dwordx4 v[96:99], v[66:67], off offset:1408
	v_mfma_f32_32x32x16_bf16 v[32:47], v[188:191], v[200:203], v[32:47]
	global_load_dwordx4 v[100:103], v[70:71], off offset:1408
	v_mfma_f32_32x32x16_bf16 v[16:31], v[196:199], v[192:195], v[16:31]
	global_load_dwordx4 v[104:107], v[72:73], off offset:1408
	v_mfma_f32_32x32x16_bf16 v[0:15], v[196:199], v[200:203], v[0:15]
	global_load_dwordx4 v[108:111], v[74:75], off offset:1408
	ds_read_b128 v[188:191], v93 offset:16384
	ds_read_b128 v[192:195], v92 offset:49152
	ds_read_b128 v[196:199], v93 offset:20480
	ds_read_b128 v[200:203], v92 offset:53248
	s_waitcnt lgkmcnt(4)
	v_mfma_f32_32x32x16_bf16 v[48:63], v[160:163], v[164:167], v[48:63]
	global_load_dwordx4 v[112:115], v[68:69], off offset:1408
	v_mfma_f32_32x32x16_bf16 v[32:47], v[160:163], v[172:175], v[32:47]
	global_load_dwordx4 v[116:119], v[76:77], off offset:1408
	v_mfma_f32_32x32x16_bf16 v[16:31], v[168:171], v[164:167], v[16:31]
	global_load_dwordx4 v[120:123], v[78:79], off offset:1408
	v_mfma_f32_32x32x16_bf16 v[0:15], v[168:171], v[172:175], v[0:15]
	global_load_dwordx4 v[124:127], v[82:83], off offset:1408
	ds_read_b128 v[160:163], v91 offset:16384
	ds_read_b128 v[164:167], v90 offset:49152
	ds_read_b128 v[168:171], v91 offset:20480
	ds_read_b128 v[172:175], v90 offset:53248
	s_waitcnt lgkmcnt(4)
	s_waitcnt vmcnt(8)
	v_mfma_f32_32x32x16_bf16 v[48:63], v[188:191], v[192:195], v[48:63]
	ds_write_b128 v87, v[128:131]
	v_mfma_f32_32x32x16_bf16 v[32:47], v[188:191], v[200:203], v[32:47]
	ds_write_b128 v87, v[132:135] offset:4096
	v_mfma_f32_32x32x16_bf16 v[16:31], v[196:199], v[192:195], v[16:31]
	ds_write_b128 v87, v[136:139] offset:8192
	v_mfma_f32_32x32x16_bf16 v[0:15], v[196:199], v[200:203], v[0:15]
	ds_write_b128 v87, v[140:143] offset:12288
	ds_read_b128 v[188:191], v89 offset:16384
	ds_read_b128 v[192:195], v88 offset:49152
	ds_read_b128 v[196:199], v89 offset:20480
	ds_read_b128 v[200:203], v88 offset:53248
	s_waitcnt lgkmcnt(8)
	v_mfma_f32_32x32x16_bf16 v[48:63], v[160:163], v[164:167], v[48:63]
	ds_write_b128 v87, v[144:147] offset:32768
	v_mfma_f32_32x32x16_bf16 v[32:47], v[160:163], v[172:175], v[32:47]
	ds_write_b128 v87, v[148:151] offset:36864
	v_mfma_f32_32x32x16_bf16 v[16:31], v[168:171], v[164:167], v[16:31]
	ds_write_b128 v87, v[152:155] offset:40960
	v_mfma_f32_32x32x16_bf16 v[0:15], v[168:171], v[172:175], v[0:15]
	ds_write_b128 v87, v[156:159] offset:45056
	s_waitcnt lgkmcnt(0)
	s_barrier
	ds_read_b128 v[160:163], v95
	ds_read_b128 v[164:167], v94 offset:32768
	ds_read_b128 v[168:171], v95 offset:4096
	ds_read_b128 v[172:175], v94 offset:36864
	v_mfma_f32_32x32x16_bf16 v[48:63], v[188:191], v[192:195], v[48:63]
	global_load_dwordx4 v[128:131], v[66:67], off offset:1536
	v_mfma_f32_32x32x16_bf16 v[32:47], v[188:191], v[200:203], v[32:47]
	global_load_dwordx4 v[132:135], v[70:71], off offset:1536
	v_mfma_f32_32x32x16_bf16 v[16:31], v[196:199], v[192:195], v[16:31]
	global_load_dwordx4 v[136:139], v[72:73], off offset:1536
	v_mfma_f32_32x32x16_bf16 v[0:15], v[196:199], v[200:203], v[0:15]
	global_load_dwordx4 v[140:143], v[74:75], off offset:1536
	ds_read_b128 v[188:191], v93
	ds_read_b128 v[192:195], v92 offset:32768
	ds_read_b128 v[196:199], v93 offset:4096
	ds_read_b128 v[200:203], v92 offset:36864
	s_waitcnt lgkmcnt(4)
	v_mfma_f32_32x32x16_bf16 v[48:63], v[160:163], v[164:167], v[48:63]
	global_load_dwordx4 v[144:147], v[68:69], off offset:1536
	v_mfma_f32_32x32x16_bf16 v[32:47], v[160:163], v[172:175], v[32:47]
	global_load_dwordx4 v[148:151], v[76:77], off offset:1536
	v_mfma_f32_32x32x16_bf16 v[16:31], v[168:171], v[164:167], v[16:31]
	global_load_dwordx4 v[152:155], v[78:79], off offset:1536
	v_mfma_f32_32x32x16_bf16 v[0:15], v[168:171], v[172:175], v[0:15]
	global_load_dwordx4 v[156:159], v[82:83], off offset:1536
	ds_read_b128 v[160:163], v91
	ds_read_b128 v[164:167], v90 offset:32768
	ds_read_b128 v[168:171], v91 offset:4096
	ds_read_b128 v[172:175], v90 offset:36864
	s_waitcnt lgkmcnt(4)
	s_waitcnt vmcnt(8)
	v_mfma_f32_32x32x16_bf16 v[48:63], v[188:191], v[192:195], v[48:63]
	ds_write_b128 v87, v[96:99] offset:16384
	v_mfma_f32_32x32x16_bf16 v[32:47], v[188:191], v[200:203], v[32:47]
	ds_write_b128 v87, v[100:103] offset:20480
	v_mfma_f32_32x32x16_bf16 v[16:31], v[196:199], v[192:195], v[16:31]
	ds_write_b128 v87, v[104:107] offset:24576
	v_mfma_f32_32x32x16_bf16 v[0:15], v[196:199], v[200:203], v[0:15]
	ds_write_b128 v87, v[108:111] offset:28672
	ds_read_b128 v[188:191], v89
	ds_read_b128 v[192:195], v88 offset:32768
	ds_read_b128 v[196:199], v89 offset:4096
	ds_read_b128 v[200:203], v88 offset:36864
	s_waitcnt lgkmcnt(8)
	v_mfma_f32_32x32x16_bf16 v[48:63], v[160:163], v[164:167], v[48:63]
	ds_write_b128 v87, v[112:115] offset:49152
	v_mfma_f32_32x32x16_bf16 v[32:47], v[160:163], v[172:175], v[32:47]
	ds_write_b128 v87, v[116:119] offset:53248
	v_mfma_f32_32x32x16_bf16 v[16:31], v[168:171], v[164:167], v[16:31]
	ds_write_b128 v87, v[120:123] offset:57344
	v_mfma_f32_32x32x16_bf16 v[0:15], v[168:171], v[172:175], v[0:15]
	ds_write_b128 v87, v[124:127] offset:61440
	s_waitcnt lgkmcnt(0)
	s_barrier
	ds_read_b128 v[160:163], v95 offset:16384
	ds_read_b128 v[164:167], v94 offset:49152
	ds_read_b128 v[168:171], v95 offset:20480
	ds_read_b128 v[172:175], v94 offset:53248
	v_mfma_f32_32x32x16_bf16 v[48:63], v[188:191], v[192:195], v[48:63]
	global_load_dwordx4 v[96:99], v[66:67], off offset:1664
	v_mfma_f32_32x32x16_bf16 v[32:47], v[188:191], v[200:203], v[32:47]
	global_load_dwordx4 v[100:103], v[70:71], off offset:1664
	v_mfma_f32_32x32x16_bf16 v[16:31], v[196:199], v[192:195], v[16:31]
	global_load_dwordx4 v[104:107], v[72:73], off offset:1664
	v_mfma_f32_32x32x16_bf16 v[0:15], v[196:199], v[200:203], v[0:15]
	global_load_dwordx4 v[108:111], v[74:75], off offset:1664
	ds_read_b128 v[188:191], v93 offset:16384
	ds_read_b128 v[192:195], v92 offset:49152
	ds_read_b128 v[196:199], v93 offset:20480
	ds_read_b128 v[200:203], v92 offset:53248
	s_waitcnt lgkmcnt(4)
	v_mfma_f32_32x32x16_bf16 v[48:63], v[160:163], v[164:167], v[48:63]
	global_load_dwordx4 v[112:115], v[68:69], off offset:1664
	v_mfma_f32_32x32x16_bf16 v[32:47], v[160:163], v[172:175], v[32:47]
	global_load_dwordx4 v[116:119], v[76:77], off offset:1664
	v_mfma_f32_32x32x16_bf16 v[16:31], v[168:171], v[164:167], v[16:31]
	global_load_dwordx4 v[120:123], v[78:79], off offset:1664
	v_mfma_f32_32x32x16_bf16 v[0:15], v[168:171], v[172:175], v[0:15]
	global_load_dwordx4 v[124:127], v[82:83], off offset:1664
	ds_read_b128 v[160:163], v91 offset:16384
	ds_read_b128 v[164:167], v90 offset:49152
	ds_read_b128 v[168:171], v91 offset:20480
	ds_read_b128 v[172:175], v90 offset:53248
	s_waitcnt lgkmcnt(4)
	s_waitcnt vmcnt(8)
	v_mfma_f32_32x32x16_bf16 v[48:63], v[188:191], v[192:195], v[48:63]
	ds_write_b128 v87, v[128:131]
	v_mfma_f32_32x32x16_bf16 v[32:47], v[188:191], v[200:203], v[32:47]
	ds_write_b128 v87, v[132:135] offset:4096
	v_mfma_f32_32x32x16_bf16 v[16:31], v[196:199], v[192:195], v[16:31]
	ds_write_b128 v87, v[136:139] offset:8192
	v_mfma_f32_32x32x16_bf16 v[0:15], v[196:199], v[200:203], v[0:15]
	ds_write_b128 v87, v[140:143] offset:12288
	ds_read_b128 v[188:191], v89 offset:16384
	ds_read_b128 v[192:195], v88 offset:49152
	ds_read_b128 v[196:199], v89 offset:20480
	ds_read_b128 v[200:203], v88 offset:53248
	s_waitcnt lgkmcnt(8)
	v_mfma_f32_32x32x16_bf16 v[48:63], v[160:163], v[164:167], v[48:63]
	ds_write_b128 v87, v[144:147] offset:32768
	v_mfma_f32_32x32x16_bf16 v[32:47], v[160:163], v[172:175], v[32:47]
	ds_write_b128 v87, v[148:151] offset:36864
	v_mfma_f32_32x32x16_bf16 v[16:31], v[168:171], v[164:167], v[16:31]
	ds_write_b128 v87, v[152:155] offset:40960
	v_mfma_f32_32x32x16_bf16 v[0:15], v[168:171], v[172:175], v[0:15]
	ds_write_b128 v87, v[156:159] offset:45056
	s_waitcnt lgkmcnt(0)
	s_barrier
	ds_read_b128 v[160:163], v95
	ds_read_b128 v[164:167], v94 offset:32768
	ds_read_b128 v[168:171], v95 offset:4096
	ds_read_b128 v[172:175], v94 offset:36864
	v_mfma_f32_32x32x16_bf16 v[48:63], v[188:191], v[192:195], v[48:63]
	global_load_dwordx4 v[128:131], v[66:67], off offset:1792
	v_mfma_f32_32x32x16_bf16 v[32:47], v[188:191], v[200:203], v[32:47]
	global_load_dwordx4 v[132:135], v[70:71], off offset:1792
	v_mfma_f32_32x32x16_bf16 v[16:31], v[196:199], v[192:195], v[16:31]
	global_load_dwordx4 v[136:139], v[72:73], off offset:1792
	v_mfma_f32_32x32x16_bf16 v[0:15], v[196:199], v[200:203], v[0:15]
	global_load_dwordx4 v[140:143], v[74:75], off offset:1792
	ds_read_b128 v[188:191], v93
	ds_read_b128 v[192:195], v92 offset:32768
	ds_read_b128 v[196:199], v93 offset:4096
	ds_read_b128 v[200:203], v92 offset:36864
	s_waitcnt lgkmcnt(4)
	v_mfma_f32_32x32x16_bf16 v[48:63], v[160:163], v[164:167], v[48:63]
	global_load_dwordx4 v[144:147], v[68:69], off offset:1792
	v_mfma_f32_32x32x16_bf16 v[32:47], v[160:163], v[172:175], v[32:47]
	global_load_dwordx4 v[148:151], v[76:77], off offset:1792
	v_mfma_f32_32x32x16_bf16 v[16:31], v[168:171], v[164:167], v[16:31]
	global_load_dwordx4 v[152:155], v[78:79], off offset:1792
	v_mfma_f32_32x32x16_bf16 v[0:15], v[168:171], v[172:175], v[0:15]
	global_load_dwordx4 v[156:159], v[82:83], off offset:1792
	ds_read_b128 v[160:163], v91
	ds_read_b128 v[164:167], v90 offset:32768
	ds_read_b128 v[168:171], v91 offset:4096
	ds_read_b128 v[172:175], v90 offset:36864
	s_waitcnt lgkmcnt(4)
	s_waitcnt vmcnt(8)
	v_mfma_f32_32x32x16_bf16 v[48:63], v[188:191], v[192:195], v[48:63]
	ds_write_b128 v87, v[96:99] offset:16384
	v_mfma_f32_32x32x16_bf16 v[32:47], v[188:191], v[200:203], v[32:47]
	ds_write_b128 v87, v[100:103] offset:20480
	v_mfma_f32_32x32x16_bf16 v[16:31], v[196:199], v[192:195], v[16:31]
	ds_write_b128 v87, v[104:107] offset:24576
	v_mfma_f32_32x32x16_bf16 v[0:15], v[196:199], v[200:203], v[0:15]
	ds_write_b128 v87, v[108:111] offset:28672
	ds_read_b128 v[188:191], v89
	ds_read_b128 v[192:195], v88 offset:32768
	ds_read_b128 v[196:199], v89 offset:4096
	ds_read_b128 v[200:203], v88 offset:36864
	s_waitcnt lgkmcnt(8)
	v_mfma_f32_32x32x16_bf16 v[48:63], v[160:163], v[164:167], v[48:63]
	ds_write_b128 v87, v[112:115] offset:49152
	v_mfma_f32_32x32x16_bf16 v[32:47], v[160:163], v[172:175], v[32:47]
	ds_write_b128 v87, v[116:119] offset:53248
	v_mfma_f32_32x32x16_bf16 v[16:31], v[168:171], v[164:167], v[16:31]
	ds_write_b128 v87, v[120:123] offset:57344
	v_mfma_f32_32x32x16_bf16 v[0:15], v[168:171], v[172:175], v[0:15]
	ds_write_b128 v87, v[124:127] offset:61440
	s_waitcnt lgkmcnt(0)
	s_barrier
	ds_read_b128 v[160:163], v95 offset:16384
	ds_read_b128 v[164:167], v94 offset:49152
	ds_read_b128 v[168:171], v95 offset:20480
	ds_read_b128 v[172:175], v94 offset:53248
	v_mfma_f32_32x32x16_bf16 v[48:63], v[188:191], v[192:195], v[48:63]
	global_load_dwordx4 v[96:99], v[66:67], off offset:1920
	v_mfma_f32_32x32x16_bf16 v[32:47], v[188:191], v[200:203], v[32:47]
	global_load_dwordx4 v[100:103], v[70:71], off offset:1920
	v_mfma_f32_32x32x16_bf16 v[16:31], v[196:199], v[192:195], v[16:31]
	global_load_dwordx4 v[104:107], v[72:73], off offset:1920
	v_mfma_f32_32x32x16_bf16 v[0:15], v[196:199], v[200:203], v[0:15]
	global_load_dwordx4 v[108:111], v[74:75], off offset:1920
	ds_read_b128 v[188:191], v93 offset:16384
	ds_read_b128 v[192:195], v92 offset:49152
	ds_read_b128 v[196:199], v93 offset:20480
	ds_read_b128 v[200:203], v92 offset:53248
	s_waitcnt lgkmcnt(4)
	v_mfma_f32_32x32x16_bf16 v[48:63], v[160:163], v[164:167], v[48:63]
	global_load_dwordx4 v[112:115], v[68:69], off offset:1920
	v_mfma_f32_32x32x16_bf16 v[32:47], v[160:163], v[172:175], v[32:47]
	global_load_dwordx4 v[116:119], v[76:77], off offset:1920
	v_mfma_f32_32x32x16_bf16 v[16:31], v[168:171], v[164:167], v[16:31]
	global_load_dwordx4 v[120:123], v[78:79], off offset:1920
	v_mfma_f32_32x32x16_bf16 v[0:15], v[168:171], v[172:175], v[0:15]
	global_load_dwordx4 v[124:127], v[82:83], off offset:1920
	ds_read_b128 v[160:163], v91 offset:16384
	ds_read_b128 v[164:167], v90 offset:49152
	ds_read_b128 v[168:171], v91 offset:20480
	ds_read_b128 v[172:175], v90 offset:53248
	s_waitcnt lgkmcnt(4)
	s_waitcnt vmcnt(8)
	v_mfma_f32_32x32x16_bf16 v[48:63], v[188:191], v[192:195], v[48:63]
	ds_write_b128 v87, v[128:131]
	v_mfma_f32_32x32x16_bf16 v[32:47], v[188:191], v[200:203], v[32:47]
	ds_write_b128 v87, v[132:135] offset:4096
	v_mfma_f32_32x32x16_bf16 v[16:31], v[196:199], v[192:195], v[16:31]
	ds_write_b128 v87, v[136:139] offset:8192
	v_mfma_f32_32x32x16_bf16 v[0:15], v[196:199], v[200:203], v[0:15]
	ds_write_b128 v87, v[140:143] offset:12288
	ds_read_b128 v[188:191], v89 offset:16384
	ds_read_b128 v[192:195], v88 offset:49152
	ds_read_b128 v[196:199], v89 offset:20480
	ds_read_b128 v[200:203], v88 offset:53248
	s_waitcnt lgkmcnt(8)
	v_mfma_f32_32x32x16_bf16 v[48:63], v[160:163], v[164:167], v[48:63]
	ds_write_b128 v87, v[144:147] offset:32768
	v_mfma_f32_32x32x16_bf16 v[32:47], v[160:163], v[172:175], v[32:47]
	ds_write_b128 v87, v[148:151] offset:36864
	v_mfma_f32_32x32x16_bf16 v[16:31], v[168:171], v[164:167], v[16:31]
	ds_write_b128 v87, v[152:155] offset:40960
	v_mfma_f32_32x32x16_bf16 v[0:15], v[168:171], v[172:175], v[0:15]
	ds_write_b128 v87, v[156:159] offset:45056
	s_waitcnt lgkmcnt(0)
	s_barrier
	ds_read_b128 v[160:163], v95
	ds_read_b128 v[164:167], v94 offset:32768
	ds_read_b128 v[168:171], v95 offset:4096
	ds_read_b128 v[172:175], v94 offset:36864
	v_mfma_f32_32x32x16_bf16 v[48:63], v[188:191], v[192:195], v[48:63]
	v_mfma_f32_32x32x16_bf16 v[32:47], v[188:191], v[200:203], v[32:47]
	v_mfma_f32_32x32x16_bf16 v[16:31], v[196:199], v[192:195], v[16:31]
	v_mfma_f32_32x32x16_bf16 v[0:15], v[196:199], v[200:203], v[0:15]
	ds_read_b128 v[188:191], v93
	ds_read_b128 v[192:195], v92 offset:32768
	ds_read_b128 v[196:199], v93 offset:4096
	ds_read_b128 v[200:203], v92 offset:36864
	s_waitcnt lgkmcnt(4)
	v_mfma_f32_32x32x16_bf16 v[48:63], v[160:163], v[164:167], v[48:63]
	v_mfma_f32_32x32x16_bf16 v[32:47], v[160:163], v[172:175], v[32:47]
	v_mfma_f32_32x32x16_bf16 v[16:31], v[168:171], v[164:167], v[16:31]
	v_mfma_f32_32x32x16_bf16 v[0:15], v[168:171], v[172:175], v[0:15]
	ds_read_b128 v[160:163], v91
	ds_read_b128 v[164:167], v90 offset:32768
	ds_read_b128 v[168:171], v91 offset:4096
	ds_read_b128 v[172:175], v90 offset:36864
	s_waitcnt lgkmcnt(4)
	s_waitcnt vmcnt(0)
	v_mfma_f32_32x32x16_bf16 v[48:63], v[188:191], v[192:195], v[48:63]
	ds_write_b128 v87, v[96:99] offset:16384
	v_mfma_f32_32x32x16_bf16 v[32:47], v[188:191], v[200:203], v[32:47]
	ds_write_b128 v87, v[100:103] offset:20480
	v_mfma_f32_32x32x16_bf16 v[16:31], v[196:199], v[192:195], v[16:31]
	ds_write_b128 v87, v[104:107] offset:24576
	v_mfma_f32_32x32x16_bf16 v[0:15], v[196:199], v[200:203], v[0:15]
	ds_write_b128 v87, v[108:111] offset:28672
	ds_read_b128 v[188:191], v89
	ds_read_b128 v[192:195], v88 offset:32768
	ds_read_b128 v[196:199], v89 offset:4096
	ds_read_b128 v[200:203], v88 offset:36864
	s_waitcnt lgkmcnt(8)
	v_mfma_f32_32x32x16_bf16 v[48:63], v[160:163], v[164:167], v[48:63]
	ds_write_b128 v87, v[112:115] offset:49152
	v_mfma_f32_32x32x16_bf16 v[32:47], v[160:163], v[172:175], v[32:47]
	ds_write_b128 v87, v[116:119] offset:53248
	v_mfma_f32_32x32x16_bf16 v[16:31], v[168:171], v[164:167], v[16:31]
	ds_write_b128 v87, v[120:123] offset:57344
	v_mfma_f32_32x32x16_bf16 v[0:15], v[168:171], v[172:175], v[0:15]
	ds_write_b128 v87, v[124:127] offset:61440
	s_waitcnt lgkmcnt(0)
	s_barrier
	ds_read_b128 v[160:163], v95 offset:16384
	ds_read_b128 v[164:167], v94 offset:49152
	ds_read_b128 v[168:171], v95 offset:20480
	ds_read_b128 v[172:175], v94 offset:53248
	v_mfma_f32_32x32x16_bf16 v[48:63], v[188:191], v[192:195], v[48:63]
	v_mfma_f32_32x32x16_bf16 v[32:47], v[188:191], v[200:203], v[32:47]
	v_mfma_f32_32x32x16_bf16 v[16:31], v[196:199], v[192:195], v[16:31]
	v_mfma_f32_32x32x16_bf16 v[0:15], v[196:199], v[200:203], v[0:15]
	ds_read_b128 v[188:191], v93 offset:16384
	ds_read_b128 v[192:195], v92 offset:49152
	ds_read_b128 v[196:199], v93 offset:20480
	ds_read_b128 v[200:203], v92 offset:53248
	s_waitcnt lgkmcnt(4)
	v_mfma_f32_32x32x16_bf16 v[48:63], v[160:163], v[164:167], v[48:63]
	v_mfma_f32_32x32x16_bf16 v[32:47], v[160:163], v[172:175], v[32:47]
	v_mfma_f32_32x32x16_bf16 v[16:31], v[168:171], v[164:167], v[16:31]
	v_mfma_f32_32x32x16_bf16 v[0:15], v[168:171], v[172:175], v[0:15]
	ds_read_b128 v[160:163], v91 offset:16384
	ds_read_b128 v[164:167], v90 offset:49152
	ds_read_b128 v[168:171], v91 offset:20480
	ds_read_b128 v[172:175], v90 offset:53248
	s_waitcnt lgkmcnt(4)
	v_mfma_f32_32x32x16_bf16 v[48:63], v[188:191], v[192:195], v[48:63]
	v_mfma_f32_32x32x16_bf16 v[32:47], v[188:191], v[200:203], v[32:47]
	v_mfma_f32_32x32x16_bf16 v[16:31], v[196:199], v[192:195], v[16:31]
	v_mfma_f32_32x32x16_bf16 v[0:15], v[196:199], v[200:203], v[0:15]
	ds_read_b128 v[188:191], v89 offset:16384
	ds_read_b128 v[192:195], v88 offset:49152
	ds_read_b128 v[196:199], v89 offset:20480
	ds_read_b128 v[200:203], v88 offset:53248
	s_waitcnt lgkmcnt(4)
	v_mfma_f32_32x32x16_bf16 v[48:63], v[160:163], v[164:167], v[48:63]
	v_mfma_f32_32x32x16_bf16 v[32:47], v[160:163], v[172:175], v[32:47]
	v_mfma_f32_32x32x16_bf16 v[16:31], v[168:171], v[164:167], v[16:31]
	v_mfma_f32_32x32x16_bf16 v[0:15], v[168:171], v[172:175], v[0:15]
	s_waitcnt lgkmcnt(0)
	s_barrier
	v_mfma_f32_32x32x16_bf16 v[48:63], v[188:191], v[192:195], v[48:63]
	v_mfma_f32_32x32x16_bf16 v[32:47], v[188:191], v[200:203], v[32:47]
	v_mfma_f32_32x32x16_bf16 v[16:31], v[196:199], v[192:195], v[16:31]
	v_mfma_f32_32x32x16_bf16 v[0:15], v[196:199], v[200:203], v[0:15]
	s_nop 15
	s_nop 0
	s_nop 0
	s_nop 0
	s_nop 0
	s_nop 0
	s_nop 0
	s_and_b32 s0, s0, 0x3fffff
	s_cmp_eq_u32 s0, 1
	v_and_b32_e32 v66, 64, v84
	v_add_u32_e32 v68, s4, v64
	v_readlane_b32 s4, v252, 37
	v_readlane_b32 s5, v252, 38
	s_nop 6
	v_and_b32_sdwa v64, v49, v81 dst_sel:DWORD dst_unused:UNUSED_PAD src0_sel:WORD_1 src1_sel:DWORD
	v_add3_u32 v49, v49, v64, s18
	v_and_b32_sdwa v64, v50, v81 dst_sel:DWORD dst_unused:UNUSED_PAD src0_sel:WORD_1 src1_sel:DWORD
	v_ashrrev_i32_e32 v69, 31, v68
	v_or3_b32 v70, v66, s1, v85
	v_lshlrev_b32_e32 v72, 2, v86
	v_ashrrev_i32_e32 v71, 31, v70
	v_or_b32_e32 v73, v68, v72
	v_lshl_add_u64 v[66:67], v[70:71], 1, s[4:5]
	v_and_b32_sdwa v71, v48, v81 dst_sel:DWORD dst_unused:UNUSED_PAD src0_sel:WORD_1 src1_sel:DWORD
	v_mad_i64_i32 v[76:77], s[4:5], v73, s17, v[66:67]
	v_add3_u32 v75, v48, v71, s18
	v_or_b32_e32 v71, 1, v73
	global_store_short_d16_hi v[76:77], v75, off
	v_mad_i64_i32 v[76:77], s[4:5], v71, s17, v[66:67]
	v_or_b32_e32 v74, 2, v73
	global_store_short_d16_hi v[76:77], v49, off
	v_mad_i64_i32 v[78:79], s[4:5], v74, s17, v[66:67]
	v_and_b32_sdwa v48, v51, v81 dst_sel:DWORD dst_unused:UNUSED_PAD src0_sel:WORD_1 src1_sel:DWORD
	v_add3_u32 v76, v50, v64, s18
	v_or_b32_e32 v50, 3, v73
	v_add3_u32 v77, v51, v48, s18
	global_store_short_d16_hi v[78:79], v76, off
	v_mad_i64_i32 v[78:79], s[4:5], v50, s17, v[66:67]
	v_or_b32_e32 v51, 8, v73
	v_and_b32_sdwa v64, v52, v81 dst_sel:DWORD dst_unused:UNUSED_PAD src0_sel:WORD_1 src1_sel:DWORD
	global_store_short_d16_hi v[78:79], v77, off
	v_mad_i64_i32 v[82:83], s[4:5], v51, s17, v[66:67]
	v_and_b32_sdwa v48, v53, v81 dst_sel:DWORD dst_unused:UNUSED_PAD src0_sel:WORD_1 src1_sel:DWORD
	v_add3_u32 v78, v52, v64, s18
	v_or_b32_e32 v52, 9, v73
	v_add3_u32 v79, v53, v48, s18
	global_store_short_d16_hi v[82:83], v78, off
	v_mad_i64_i32 v[82:83], s[4:5], v52, s17, v[66:67]
	v_or_b32_e32 v53, 10, v73
	v_and_b32_sdwa v64, v54, v81 dst_sel:DWORD dst_unused:UNUSED_PAD src0_sel:WORD_1 src1_sel:DWORD
	global_store_short_d16_hi v[82:83], v79, off
	v_mad_i64_i32 v[84:85], s[4:5], v53, s17, v[66:67]
	v_and_b32_sdwa v48, v55, v81 dst_sel:DWORD dst_unused:UNUSED_PAD src0_sel:WORD_1 src1_sel:DWORD
	v_add3_u32 v82, v54, v64, s18
	v_or_b32_e32 v54, 11, v73
	v_add3_u32 v83, v55, v48, s18
	global_store_short_d16_hi v[84:85], v82, off
	v_mad_i64_i32 v[84:85], s[4:5], v54, s17, v[66:67]
	v_or_b32_e32 v55, 16, v73
	v_and_b32_sdwa v64, v56, v81 dst_sel:DWORD dst_unused:UNUSED_PAD src0_sel:WORD_1 src1_sel:DWORD
	global_store_short_d16_hi v[84:85], v83, off
	v_mad_i64_i32 v[86:87], s[4:5], v55, s17, v[66:67]
	v_and_b32_sdwa v48, v57, v81 dst_sel:DWORD dst_unused:UNUSED_PAD src0_sel:WORD_1 src1_sel:DWORD
	v_add3_u32 v84, v56, v64, s18
	v_or_b32_e32 v56, 17, v73
	v_add3_u32 v85, v57, v48, s18
	global_store_short_d16_hi v[86:87], v84, off
	v_mad_i64_i32 v[86:87], s[4:5], v56, s17, v[66:67]
	v_or_b32_e32 v57, 18, v73
	v_and_b32_sdwa v64, v58, v81 dst_sel:DWORD dst_unused:UNUSED_PAD src0_sel:WORD_1 src1_sel:DWORD
	global_store_short_d16_hi v[86:87], v85, off
	v_mad_i64_i32 v[88:89], s[4:5], v57, s17, v[66:67]
	v_and_b32_sdwa v48, v59, v81 dst_sel:DWORD dst_unused:UNUSED_PAD src0_sel:WORD_1 src1_sel:DWORD
	v_add3_u32 v86, v58, v64, s18
	v_or_b32_e32 v58, 19, v73
	v_add3_u32 v87, v59, v48, s18
	global_store_short_d16_hi v[88:89], v86, off
	v_mad_i64_i32 v[88:89], s[4:5], v58, s17, v[66:67]
	v_or_b32_e32 v59, 24, v73
	v_and_b32_sdwa v64, v60, v81 dst_sel:DWORD dst_unused:UNUSED_PAD src0_sel:WORD_1 src1_sel:DWORD
	global_store_short_d16_hi v[88:89], v87, off
	v_mad_i64_i32 v[90:91], s[4:5], v59, s17, v[66:67]
	v_and_b32_sdwa v48, v61, v81 dst_sel:DWORD dst_unused:UNUSED_PAD src0_sel:WORD_1 src1_sel:DWORD
	v_add3_u32 v88, v60, v64, s18
	v_or_b32_e32 v60, 25, v73
	v_add3_u32 v89, v61, v48, s18
	global_store_short_d16_hi v[90:91], v88, off
	v_mad_i64_i32 v[90:91], s[4:5], v60, s17, v[66:67]
	v_or_b32_e32 v61, 26, v73
	v_and_b32_sdwa v64, v62, v81 dst_sel:DWORD dst_unused:UNUSED_PAD src0_sel:WORD_1 src1_sel:DWORD
	global_store_short_d16_hi v[90:91], v89, off
	v_mad_i64_i32 v[92:93], s[4:5], v61, s17, v[66:67]
	v_add3_u32 v90, v62, v64, s18
	v_or_b32_e32 v62, 27, v73
	v_and_b32_sdwa v48, v63, v81 dst_sel:DWORD dst_unused:UNUSED_PAD src0_sel:WORD_1 src1_sel:DWORD
	global_store_short_d16_hi v[92:93], v90, off
	v_mad_i64_i32 v[92:93], s[4:5], v62, s17, v[66:67]
	v_add3_u32 v63, v63, v48, s18
	s_cselect_b64 s[4:5], -1, 0
	s_cmp_lg_u32 s0, 1
	v_mul_lo_u32 v64, v70, s19
	v_lshlrev_b32_e32 v48, 1, v72
	global_store_short_d16_hi v[92:93], v63, off
	s_cbranch_scc1 .LBB0_1856
	v_readlane_b32 s0, v252, 0
	v_readlane_b32 s1, v252, 1
	v_lshrrev_b32_e32 v92, 16, v77
	v_lshrrev_b32_e32 v93, 16, v76
	v_lshl_add_u64 v[76:77], v[64:65], 1, s[0:1]
	v_lshrrev_b32_e32 v91, 16, v49
	v_lshl_add_u64 v[76:77], v[68:69], 1, v[76:77]
	v_mov_b32_e32 v49, v65
	v_lshl_add_u64 v[76:77], v[76:77], 0, v[48:49]
	v_lshrrev_b32_e32 v75, 16, v75
	v_lshrrev_b32_e32 v94, 16, v79
	v_lshrrev_b32_e32 v95, 16, v78
	v_lshl_add_u64 v[78:79], v[76:77], 0, s[2:3]
	v_add_co_u32_e32 v76, vcc, s21, v76
	v_lshrrev_b32_e32 v96, 16, v83
	v_lshrrev_b32_e32 v97, 16, v82
	v_perm_b32 v83, v92, v93, s20
	v_perm_b32 v82, v91, v75, s20
	v_addc_co_u32_e32 v77, vcc, 0, v77, vcc
	v_lshrrev_b32_e32 v85, 16, v85
	v_lshrrev_b32_e32 v84, 16, v84
	v_lshrrev_b32_e32 v87, 16, v87
	v_lshrrev_b32_e32 v86, 16, v86
	global_store_dwordx2 v[76:77], v[82:83], off offset:2048
	v_perm_b32 v77, v96, v97, s20
	v_perm_b32 v76, v94, v95, s20
	v_lshrrev_b32_e32 v89, 16, v89
	v_lshrrev_b32_e32 v88, 16, v88
	v_lshrrev_b32_e32 v63, 16, v63
	v_lshrrev_b32_e32 v90, 16, v90
	global_store_dwordx2 v[78:79], v[76:77], off offset:16
	v_perm_b32 v77, v87, v86, s20
	v_perm_b32 v76, v85, v84, s20
	global_store_dwordx2 v[78:79], v[76:77], off offset:32
	v_perm_b32 v77, v63, v90, s20
	v_perm_b32 v76, v89, v88, s20
	global_store_dwordx2 v[78:79], v[76:77], off offset:48
